# GEMM K-loop: 16 VALU 64-bit address adds replaced by saddr-form LDS-DMA loads with scalar base updates
# speedup vs baseline: 1.0035x; 1.0035x over previous
; #define PG8_STAGE(bufoff, gbase, voff) do { _Pragma("unroll") for (int _i = 0; _i < 2; ++_i) \
;         __builtin_amdgcn_global_load_lds((const unsigned*)((const char*)(gbase) + (voff)[_i]), (PG8_LAS unsigned*)(lds + (bufoff) + ldsw + _i * 8192), 16, 0, 0); } while (0)
; #define PG8_LDA(dst, b, h) do { _Pragma("unroll") for (int m = 0; m < 4; ++m) _Pragma("unroll") for (int k = 0; k < 2; ++k) dst[m][k] = *(const PG8_LAS bf16x8*)(lds + PG8_SA(b, h) + aoff + m * 2048 + k * 1024); } while (0)
; #define PG8_LDB(dst, b, h) do { _Pragma("unroll") for (int n = 0; n < 2; ++n) _Pragma("unroll") for (int k = 0; k < 2; ++k) dst[n][k] = *(const PG8_LAS bf16x8*)(lds + PG8_SB(b, h) + boff + n * 2048 + k * 1024); } while (0)
; #define PG8_MMA(ai, bj, At, Bt) do { __builtin_amdgcn_s_setprio(1); _Pragma("unroll") for (int m = 0; m < 4; ++m) _Pragma("unroll") for (int n = 0; n < 2; ++n) _Pragma("unroll") for (int k = 0; k < 2; ++k) \
;         acc[ai][bj][m][n] = __builtin_amdgcn_mfma_f32_16x16x32_bf16(Bt[n][k], At[m][k], acc[ai][bj][m][n], 0, 0, 0); __builtin_amdgcn_s_setprio(0); } while (0)
; #define PG8_WAIT_V(n) asm volatile("s_waitcnt vmcnt(" #n ")" ::: "memory")
; #define PG8_WAIT_L(n) asm volatile("s_waitcnt lgkmcnt(" #n ")" ::: "memory")
; #define PG8_BAR __builtin_amdgcn_s_barrier()
; #define PG8_SCHED __builtin_amdgcn_sched_barrier(0)
; template <class Epi, class Sched, bool STAMP = false>
; __device__ __forceinline__ void gemm_phase(PG8_LAS unsigned char* lds, const Gemm g, const Sched& S, const Epi& E, unsigned long long* stamps) {
;     ...
;             PG8_LDB(B0, 0, 0); PG8_SCHED; PG8_LDA(At, 0, 0); PG8_STAGE(PG8_SA(1, 1), a1 + hstep, voffA);
;             PG8_WAIT_L(8); PG8_BAR; PG8_WAIT_L(0); PG8_MMA(0, 0, At, B0); PG8_BAR; PG8_SCHED;
;             PG8_LDB(B1, 0, 1); PG8_STAGE(PG8_SB(0, 0), b2, voffB);
;             PG8_BAR; PG8_WAIT_L(0); PG8_MMA(0, 1, At, B1); PG8_BAR;
;             PG8_LDA(At, 0, 1); PG8_STAGE(PG8_SA(0, 0), a2, voffA);
;             PG8_BAR; PG8_WAIT_L(0); PG8_MMA(1, 0, At, B0); PG8_BAR; PG8_SCHED;
;             PG8_STAGE(PG8_SB(0, 1), b2 + hstep, voffB);
;             PG8_WAIT_V(6); PG8_BAR; PG8_MMA(1, 1, At, B1); PG8_BAR;
.LBB0_745:
	s_add_i32 s93, s22, 2
	s_add_u32 s38, s0, 0x80
	s_addc_u32 s23, s1, 0
	s_add_i32 s62, 0, 0x10000
	v_add_u32_e32 v142, s62, v217
	ds_read_b128 v[130:133], v142
	ds_read_b128 v[134:137], v142 offset:1024
	ds_read_b128 v[138:141], v142 offset:2048
	ds_read_b128 v[142:145], v142 offset:3072
	s_cmp_eq_u32 s4, s22
	s_cselect_b32 s22, s90, s38
	s_cselect_b32 s23, s91, s23
	s_cselect_b32 s39, s31, s89
	s_cselect_b32 s38, s30, s88
	s_add_i32 m0, s80, 0xc000
	ds_read_b128 v[146:149], v218
	ds_read_b128 v[150:153], v218 offset:1024
	ds_read_b128 v[154:157], v218 offset:2048
	ds_read_b128 v[158:161], v218 offset:3072
	ds_read_b128 v[176:179], v218 offset:4096
	ds_read_b128 v[180:183], v218 offset:5120
	ds_read_b128 v[184:187], v218 offset:6144
	ds_read_b128 v[188:191], v218 offset:7168
	global_load_lds_dwordx4 v172, s[0:1]
	s_add_i32 m0, s80, 0xe000
	s_nop 0
	global_load_lds_dwordx4 v174, s[0:1]
	s_waitcnt lgkmcnt(8)
	s_barrier
	s_waitcnt lgkmcnt(0)
	s_waitcnt lgkmcnt(0)
	v_mfma_f32_16x16x32_bf16 v[126:129], v[130:133], v[146:149], v[126:129]
	v_mfma_f32_16x16x32_bf16 v[122:125], v[138:141], v[146:149], v[122:125]
	v_mfma_f32_16x16x32_bf16 v[118:121], v[130:133], v[154:157], v[118:121]
	v_mfma_f32_16x16x32_bf16 v[114:117], v[138:141], v[154:157], v[114:117]
	v_mfma_f32_16x16x32_bf16 v[102:105], v[130:133], v[176:179], v[102:105]
	v_mfma_f32_16x16x32_bf16 v[98:101], v[138:141], v[176:179], v[98:101]
	v_mfma_f32_16x16x32_bf16 v[86:89], v[130:133], v[184:187], v[86:89]
	v_mfma_f32_16x16x32_bf16 v[82:85], v[138:141], v[184:187], v[82:85]
	v_mfma_f32_16x16x32_bf16 v[126:129], v[134:137], v[150:153], v[126:129]
	v_mfma_f32_16x16x32_bf16 v[122:125], v[142:145], v[150:153], v[122:125]
	v_mfma_f32_16x16x32_bf16 v[118:121], v[134:137], v[158:161], v[118:121]
	v_mfma_f32_16x16x32_bf16 v[114:117], v[142:145], v[158:161], v[114:117]
	v_mfma_f32_16x16x32_bf16 v[102:105], v[134:137], v[180:183], v[102:105]
	v_mfma_f32_16x16x32_bf16 v[98:101], v[142:145], v[180:183], v[98:101]
	v_mfma_f32_16x16x32_bf16 v[86:89], v[134:137], v[188:191], v[86:89]
	v_mfma_f32_16x16x32_bf16 v[82:85], v[142:145], v[188:191], v[82:85]
	s_barrier
	s_add_i32 s63, 0, 0x14000
	s_add_i32 s62, s62, s79
	v_add_u32_e32 v204, s63, v217
	s_add_u32 s98, s38, s10
	s_addc_u32 s99, s39, s11
	s_mov_b32 m0, s62
	ds_read_b128 v[192:195], v204
	ds_read_b128 v[196:199], v204 offset:1024
	ds_read_b128 v[200:203], v204 offset:2048
	ds_read_b128 v[204:207], v204 offset:3072
	global_load_lds_dwordx4 v164, s[38:39]
	s_add_i32 m0, s62, 0x2000
	s_nop 0
	global_load_lds_dwordx4 v170, s[38:39]
	s_barrier
	s_waitcnt lgkmcnt(0)
	s_waitcnt lgkmcnt(0)
	v_mfma_f32_16x16x32_bf16 v[110:113], v[192:195], v[146:149], v[110:113]
	v_mfma_f32_16x16x32_bf16 v[106:109], v[200:203], v[146:149], v[106:109]
	v_mfma_f32_16x16x32_bf16 v[94:97], v[192:195], v[154:157], v[94:97]
	v_mfma_f32_16x16x32_bf16 v[90:93], v[200:203], v[154:157], v[90:93]
	v_mfma_f32_16x16x32_bf16 v[78:81], v[192:195], v[176:179], v[78:81]
	v_mfma_f32_16x16x32_bf16 v[74:77], v[200:203], v[176:179], v[74:77]
	v_mfma_f32_16x16x32_bf16 v[70:73], v[192:195], v[184:187], v[70:73]
	v_mfma_f32_16x16x32_bf16 v[66:69], v[200:203], v[184:187], v[66:69]
	v_mfma_f32_16x16x32_bf16 v[110:113], v[196:199], v[150:153], v[110:113]
	v_mfma_f32_16x16x32_bf16 v[106:109], v[204:207], v[150:153], v[106:109]
	v_mfma_f32_16x16x32_bf16 v[94:97], v[196:199], v[158:161], v[94:97]
	v_mfma_f32_16x16x32_bf16 v[90:93], v[204:207], v[158:161], v[90:93]
	v_mfma_f32_16x16x32_bf16 v[78:81], v[196:199], v[180:183], v[78:81]
	v_mfma_f32_16x16x32_bf16 v[74:77], v[204:207], v[180:183], v[74:77]
	v_mfma_f32_16x16x32_bf16 v[70:73], v[196:199], v[188:191], v[70:73]
	v_mfma_f32_16x16x32_bf16 v[66:69], v[204:207], v[188:191], v[66:69]
	s_mov_b32 m0, s80
	s_add_u32 s100, s22, s10
	s_addc_u32 s101, s23, s11
	s_barrier
	ds_read_b128 v[146:149], v218 offset:16384
	ds_read_b128 v[150:153], v218 offset:17408
	ds_read_b128 v[154:157], v218 offset:18432
	ds_read_b128 v[158:161], v218 offset:19456
	ds_read_b128 v[176:179], v218 offset:20480
	ds_read_b128 v[180:183], v218 offset:21504
	ds_read_b128 v[184:187], v218 offset:22528
	ds_read_b128 v[188:191], v218 offset:23552
	global_load_lds_dwordx4 v162, s[22:23]
	s_mov_b32 m0, s81
	s_nop 0
	global_load_lds_dwordx4 v166, s[22:23]
	s_barrier
	s_waitcnt lgkmcnt(0)
	s_waitcnt lgkmcnt(0)
	v_mfma_f32_16x16x32_bf16 v[62:65], v[130:133], v[146:149], v[62:65]
	v_mfma_f32_16x16x32_bf16 v[58:61], v[138:141], v[146:149], v[58:61]
	v_mfma_f32_16x16x32_bf16 v[54:57], v[130:133], v[154:157], v[54:57]
	v_mfma_f32_16x16x32_bf16 v[50:53], v[138:141], v[154:157], v[50:53]
	v_mfma_f32_16x16x32_bf16 v[38:41], v[130:133], v[176:179], v[38:41]
	v_mfma_f32_16x16x32_bf16 v[34:37], v[138:141], v[176:179], v[34:37]
	v_mfma_f32_16x16x32_bf16 v[22:25], v[130:133], v[184:187], v[22:25]
	v_mfma_f32_16x16x32_bf16 v[18:21], v[138:141], v[184:187], v[18:21]
	v_mfma_f32_16x16x32_bf16 v[62:65], v[134:137], v[150:153], v[62:65]
	v_mfma_f32_16x16x32_bf16 v[58:61], v[142:145], v[150:153], v[58:61]
	v_mfma_f32_16x16x32_bf16 v[54:57], v[134:137], v[158:161], v[54:57]
	v_mfma_f32_16x16x32_bf16 v[50:53], v[142:145], v[158:161], v[50:53]
	v_mfma_f32_16x16x32_bf16 v[38:41], v[134:137], v[180:183], v[38:41]
	v_mfma_f32_16x16x32_bf16 v[34:37], v[142:145], v[180:183], v[34:37]
	v_mfma_f32_16x16x32_bf16 v[22:25], v[134:137], v[188:191], v[22:25]
	v_mfma_f32_16x16x32_bf16 v[18:21], v[142:145], v[188:191], v[18:21]
	s_barrier
	s_add_u32 s38, s38, s94
	s_addc_u32 s39, s39, 0
	s_add_i32 s62, s63, s79
	s_mov_b32 m0, s62
	global_load_lds_dwordx4 v164, s[38:39]
	s_add_i32 m0, s62, 0x2000
	s_nop 0
	global_load_lds_dwordx4 v170, s[38:39]
	s_waitcnt vmcnt(6)
	s_barrier
; #define PG8_STAGE(bufoff, gbase, voff) do { _Pragma("unroll") for (int _i = 0; _i < 2; ++_i) \
;         __builtin_amdgcn_global_load_lds((const unsigned*)((const char*)(gbase) + (voff)[_i]), (PG8_LAS unsigned*)(lds + (bufoff) + ldsw + _i * 8192), 16, 0, 0); } while (0)
; #define PG8_LDA(dst, b, h) do { _Pragma("unroll") for (int m = 0; m < 4; ++m) _Pragma("unroll") for (int k = 0; k < 2; ++k) dst[m][k] = *(const PG8_LAS bf16x8*)(lds + PG8_SA(b, h) + aoff + m * 2048 + k * 1024); } while (0)
; #define PG8_LDB(dst, b, h) do { _Pragma("unroll") for (int n = 0; n < 2; ++n) _Pragma("unroll") for (int k = 0; k < 2; ++k) dst[n][k] = *(const PG8_LAS bf16x8*)(lds + PG8_SB(b, h) + boff + n * 2048 + k * 1024); } while (0)
; #define PG8_MMA(ai, bj, At, Bt) do { __builtin_amdgcn_s_setprio(1); _Pragma("unroll") for (int m = 0; m < 4; ++m) _Pragma("unroll") for (int n = 0; n < 2; ++n) _Pragma("unroll") for (int k = 0; k < 2; ++k) \
;         acc[ai][bj][m][n] = __builtin_amdgcn_mfma_f32_16x16x32_bf16(Bt[n][k], At[m][k], acc[ai][bj][m][n], 0, 0, 0); __builtin_amdgcn_s_setprio(0); } while (0)
; #define PG8_WAIT_V(n) asm volatile("s_waitcnt vmcnt(" #n ")" ::: "memory")
; #define PG8_WAIT_L(n) asm volatile("s_waitcnt lgkmcnt(" #n ")" ::: "memory")
; #define PG8_BAR __builtin_amdgcn_s_barrier()
; #define PG8_SCHED __builtin_amdgcn_sched_barrier(0)
; template <class Epi, class Sched, bool STAMP = false>
; __device__ __forceinline__ void gemm_phase(PG8_LAS unsigned char* lds, const Gemm g, const Sched& S, const Epi& E, unsigned long long* stamps) {
;     ...
;             PG8_WAIT_V(6); PG8_BAR; PG8_MMA(1, 1, At, B1); PG8_BAR;
;             PG8_LDB(B0, 1, 0); PG8_SCHED; PG8_LDA(At, 1, 0); PG8_STAGE(PG8_SA(0, 1), a2 + hstep, voffA);
;             PG8_WAIT_L(8); PG8_BAR; PG8_WAIT_L(0); PG8_MMA(0, 0, At, B0); PG8_BAR; PG8_SCHED;
;             PG8_LDB(B1, 1, 1); PG8_STAGE(PG8_SB(1, 0), b3, voffB);
;             PG8_BAR; PG8_WAIT_L(0); PG8_MMA(0, 1, At, B1); PG8_BAR;
;             PG8_LDA(At, 1, 1); PG8_STAGE(PG8_SA(1, 0), a3, voffA);
;             PG8_BAR; PG8_WAIT_L(0); PG8_MMA(1, 0, At, B0); PG8_BAR; PG8_SCHED;
	v_mfma_f32_16x16x32_bf16 v[46:49], v[192:195], v[146:149], v[46:49]
	v_mfma_f32_16x16x32_bf16 v[42:45], v[200:203], v[146:149], v[42:45]
	v_mfma_f32_16x16x32_bf16 v[30:33], v[192:195], v[154:157], v[30:33]
	v_mfma_f32_16x16x32_bf16 v[26:29], v[200:203], v[154:157], v[26:29]
	v_mfma_f32_16x16x32_bf16 v[14:17], v[192:195], v[176:179], v[14:17]
	v_mfma_f32_16x16x32_bf16 v[10:13], v[200:203], v[176:179], v[10:13]
	v_mfma_f32_16x16x32_bf16 v[6:9], v[192:195], v[184:187], v[6:9]
	v_mfma_f32_16x16x32_bf16 v[2:5], v[200:203], v[184:187], v[2:5]
	v_mfma_f32_16x16x32_bf16 v[46:49], v[196:199], v[150:153], v[46:49]
	v_mfma_f32_16x16x32_bf16 v[42:45], v[204:207], v[150:153], v[42:45]
	v_mfma_f32_16x16x32_bf16 v[30:33], v[196:199], v[158:161], v[30:33]
	v_mfma_f32_16x16x32_bf16 v[26:29], v[204:207], v[158:161], v[26:29]
	v_mfma_f32_16x16x32_bf16 v[14:17], v[196:199], v[180:183], v[14:17]
	v_mfma_f32_16x16x32_bf16 v[10:13], v[204:207], v[180:183], v[10:13]
	v_mfma_f32_16x16x32_bf16 v[6:9], v[196:199], v[188:191], v[6:9]
	v_mfma_f32_16x16x32_bf16 v[2:5], v[204:207], v[188:191], v[2:5]
	s_add_i32 s38, 0, 0x18000
	v_add_u32_e32 v142, s38, v217
	s_barrier
	ds_read_b128 v[130:133], v142
	ds_read_b128 v[134:137], v142 offset:1024
	ds_read_b128 v[138:141], v142 offset:2048
	ds_read_b128 v[142:145], v142 offset:3072
	s_add_u32 s22, s22, s94
	s_addc_u32 s23, s23, 0
	s_mov_b32 m0, s84
	ds_read_b128 v[146:149], v218 offset:32768
	ds_read_b128 v[150:153], v218 offset:33792
	ds_read_b128 v[154:157], v218 offset:34816
	ds_read_b128 v[158:161], v218 offset:35840
	ds_read_b128 v[176:179], v218 offset:36864
	ds_read_b128 v[180:183], v218 offset:37888
	ds_read_b128 v[184:187], v218 offset:38912
	ds_read_b128 v[188:191], v218 offset:39936
	global_load_lds_dwordx4 v162, s[22:23]
	s_mov_b32 m0, s85
	s_nop 0
	global_load_lds_dwordx4 v166, s[22:23]
	s_waitcnt lgkmcnt(8)
	s_barrier
	s_waitcnt lgkmcnt(0)
	s_waitcnt lgkmcnt(0)
	v_mfma_f32_16x16x32_bf16 v[126:129], v[130:133], v[146:149], v[126:129]
	v_mfma_f32_16x16x32_bf16 v[122:125], v[138:141], v[146:149], v[122:125]
	v_mfma_f32_16x16x32_bf16 v[118:121], v[130:133], v[154:157], v[118:121]
	v_mfma_f32_16x16x32_bf16 v[114:117], v[138:141], v[154:157], v[114:117]
	v_mfma_f32_16x16x32_bf16 v[102:105], v[130:133], v[176:179], v[102:105]
	v_mfma_f32_16x16x32_bf16 v[98:101], v[138:141], v[176:179], v[98:101]
	v_mfma_f32_16x16x32_bf16 v[86:89], v[130:133], v[184:187], v[86:89]
	v_mfma_f32_16x16x32_bf16 v[82:85], v[138:141], v[184:187], v[82:85]
	v_mfma_f32_16x16x32_bf16 v[126:129], v[134:137], v[150:153], v[126:129]
	v_mfma_f32_16x16x32_bf16 v[122:125], v[142:145], v[150:153], v[122:125]
	v_mfma_f32_16x16x32_bf16 v[118:121], v[134:137], v[158:161], v[118:121]
	v_mfma_f32_16x16x32_bf16 v[114:117], v[142:145], v[158:161], v[114:117]
	v_mfma_f32_16x16x32_bf16 v[102:105], v[134:137], v[180:183], v[102:105]
	v_mfma_f32_16x16x32_bf16 v[98:101], v[142:145], v[180:183], v[98:101]
	v_mfma_f32_16x16x32_bf16 v[86:89], v[134:137], v[188:191], v[86:89]
	v_mfma_f32_16x16x32_bf16 v[82:85], v[142:145], v[188:191], v[82:85]
	s_barrier
	s_add_i32 s22, s38, s79
	v_add_u32_e32 v204, s35, v217
	s_mov_b32 m0, s22
	ds_read_b128 v[192:195], v204
	ds_read_b128 v[196:199], v204 offset:1024
	ds_read_b128 v[200:203], v204 offset:2048
	ds_read_b128 v[204:207], v204 offset:3072
	global_load_lds_dwordx4 v164, s[98:99]
	s_add_i32 m0, s22, 0x2000
	s_nop 0
	global_load_lds_dwordx4 v170, s[98:99]
	s_add_u32 s98, s98, s94
	s_addc_u32 s99, s99, 0
	s_barrier
	s_waitcnt lgkmcnt(0)
	s_waitcnt lgkmcnt(0)
	v_mfma_f32_16x16x32_bf16 v[110:113], v[192:195], v[146:149], v[110:113]
	v_mfma_f32_16x16x32_bf16 v[106:109], v[200:203], v[146:149], v[106:109]
	v_mfma_f32_16x16x32_bf16 v[94:97], v[192:195], v[154:157], v[94:97]
	v_mfma_f32_16x16x32_bf16 v[90:93], v[200:203], v[154:157], v[90:93]
	v_mfma_f32_16x16x32_bf16 v[78:81], v[192:195], v[176:179], v[78:81]
	v_mfma_f32_16x16x32_bf16 v[74:77], v[200:203], v[176:179], v[74:77]
	v_mfma_f32_16x16x32_bf16 v[70:73], v[192:195], v[184:187], v[70:73]
	v_mfma_f32_16x16x32_bf16 v[66:69], v[200:203], v[184:187], v[66:69]
	v_mfma_f32_16x16x32_bf16 v[110:113], v[196:199], v[150:153], v[110:113]
	v_mfma_f32_16x16x32_bf16 v[106:109], v[204:207], v[150:153], v[106:109]
	v_mfma_f32_16x16x32_bf16 v[94:97], v[196:199], v[158:161], v[94:97]
	v_mfma_f32_16x16x32_bf16 v[90:93], v[204:207], v[158:161], v[90:93]
	v_mfma_f32_16x16x32_bf16 v[78:81], v[196:199], v[180:183], v[78:81]
	v_mfma_f32_16x16x32_bf16 v[74:77], v[204:207], v[180:183], v[74:77]
	v_mfma_f32_16x16x32_bf16 v[70:73], v[196:199], v[188:191], v[70:73]
	v_mfma_f32_16x16x32_bf16 v[66:69], v[204:207], v[188:191], v[66:69]
	s_mov_b32 m0, s33
	s_barrier
	ds_read_b128 v[146:149], v218 offset:49152
	ds_read_b128 v[150:153], v218 offset:50176
	ds_read_b128 v[154:157], v218 offset:51200
	ds_read_b128 v[158:161], v218 offset:52224
	ds_read_b128 v[176:179], v218 offset:53248
	ds_read_b128 v[180:183], v218 offset:54272
	ds_read_b128 v[184:187], v218 offset:55296
	ds_read_b128 v[188:191], v218 offset:56320
	global_load_lds_dwordx4 v162, s[100:101]
	s_mov_b32 m0, s28
	s_nop 0
	global_load_lds_dwordx4 v166, s[100:101]
	s_barrier
; #define PG8_STAGE(bufoff, gbase, voff) do { _Pragma("unroll") for (int _i = 0; _i < 2; ++_i) \
;         __builtin_amdgcn_global_load_lds((const unsigned*)((const char*)(gbase) + (voff)[_i]), (PG8_LAS unsigned*)(lds + (bufoff) + ldsw + _i * 8192), 16, 0, 0); } while (0)
; #define PG8_MMA(ai, bj, At, Bt) do { __builtin_amdgcn_s_setprio(1); _Pragma("unroll") for (int m = 0; m < 4; ++m) _Pragma("unroll") for (int n = 0; n < 2; ++n) _Pragma("unroll") for (int k = 0; k < 2; ++k) \
;         acc[ai][bj][m][n] = __builtin_amdgcn_mfma_f32_16x16x32_bf16(Bt[n][k], At[m][k], acc[ai][bj][m][n], 0, 0, 0); __builtin_amdgcn_s_setprio(0); } while (0)
; #define PG8_WAIT_V(n) asm volatile("s_waitcnt vmcnt(" #n ")" ::: "memory")
; #define PG8_WAIT_L(n) asm volatile("s_waitcnt lgkmcnt(" #n ")" ::: "memory")
; #define PG8_BAR __builtin_amdgcn_s_barrier()
; #define PG8_SCHED __builtin_amdgcn_sched_barrier(0)
; template <class Epi, class Sched, bool STAMP = false>
; __device__ __forceinline__ void gemm_phase(PG8_LAS unsigned char* lds, const Gemm g, const Sched& S, const Epi& E, unsigned long long* stamps) {
;     ...
;             PG8_BAR; PG8_WAIT_L(0); PG8_MMA(1, 0, At, B0); PG8_BAR; PG8_SCHED;
;             PG8_STAGE(PG8_SB(1, 1), b3 + hstep, voffB);
;             PG8_WAIT_V(6); PG8_BAR; PG8_MMA(1, 1, At, B1); PG8_BAR;
;         }
;   DI void operator()(const f32x4 (&acc)[2][2][4][2], const pg8::Unit& u, int wr, int wc, int fr, int fq) const {
;     ...
; #pragma unroll
;       for (int ai = 0; ai < 2; ++ai) {
;         uint4 gs[4][2];
; #pragma unroll
;         for (int m = 0; m < 4; ++m)
; #pragma unroll
;           for (int bj = 0; bj < 2; ++bj)
;             gs[m][bj] = *(const uint4*)(o0 + (size_t)(row0 + ai * 128 + m * 16) * DFF + col0 + bj * 128);
;         __builtin_amdgcn_sched_barrier(0);
	s_waitcnt lgkmcnt(0)
	s_waitcnt lgkmcnt(0)
	v_mfma_f32_16x16x32_bf16 v[62:65], v[130:133], v[146:149], v[62:65]
	v_mfma_f32_16x16x32_bf16 v[58:61], v[138:141], v[146:149], v[58:61]
	v_mfma_f32_16x16x32_bf16 v[54:57], v[130:133], v[154:157], v[54:57]
	v_mfma_f32_16x16x32_bf16 v[50:53], v[138:141], v[154:157], v[50:53]
	v_mfma_f32_16x16x32_bf16 v[38:41], v[130:133], v[176:179], v[38:41]
	v_mfma_f32_16x16x32_bf16 v[34:37], v[138:141], v[176:179], v[34:37]
	v_mfma_f32_16x16x32_bf16 v[22:25], v[130:133], v[184:187], v[22:25]
	v_mfma_f32_16x16x32_bf16 v[18:21], v[138:141], v[184:187], v[18:21]
	v_mfma_f32_16x16x32_bf16 v[62:65], v[134:137], v[150:153], v[62:65]
	v_mfma_f32_16x16x32_bf16 v[58:61], v[142:145], v[150:153], v[58:61]
	v_mfma_f32_16x16x32_bf16 v[54:57], v[134:137], v[158:161], v[54:57]
	v_mfma_f32_16x16x32_bf16 v[50:53], v[142:145], v[158:161], v[50:53]
	v_mfma_f32_16x16x32_bf16 v[38:41], v[134:137], v[180:183], v[38:41]
	v_mfma_f32_16x16x32_bf16 v[34:37], v[142:145], v[180:183], v[34:37]
	v_mfma_f32_16x16x32_bf16 v[22:25], v[134:137], v[188:191], v[22:25]
	v_mfma_f32_16x16x32_bf16 v[18:21], v[142:145], v[188:191], v[18:21]
	s_barrier
	s_add_i32 s22, s35, s79
	s_mov_b32 m0, s22
	s_nop 0
	global_load_lds_dwordx4 v164, s[98:99]
	s_add_i32 m0, s22, 0x2000
	s_nop 0
	global_load_lds_dwordx4 v170, s[98:99]
	s_waitcnt vmcnt(6)
	s_barrier
	v_mfma_f32_16x16x32_bf16 v[46:49], v[192:195], v[146:149], v[46:49]
	v_mfma_f32_16x16x32_bf16 v[42:45], v[200:203], v[146:149], v[42:45]
	v_mfma_f32_16x16x32_bf16 v[30:33], v[192:195], v[154:157], v[30:33]
	v_mfma_f32_16x16x32_bf16 v[26:29], v[200:203], v[154:157], v[26:29]
	v_mfma_f32_16x16x32_bf16 v[14:17], v[192:195], v[176:179], v[14:17]
	v_mfma_f32_16x16x32_bf16 v[10:13], v[200:203], v[176:179], v[10:13]
	v_mfma_f32_16x16x32_bf16 v[6:9], v[192:195], v[184:187], v[6:9]
	v_mfma_f32_16x16x32_bf16 v[2:5], v[200:203], v[184:187], v[2:5]
	v_mfma_f32_16x16x32_bf16 v[46:49], v[196:199], v[150:153], v[46:49]
	v_mfma_f32_16x16x32_bf16 v[42:45], v[204:207], v[150:153], v[42:45]
	v_mfma_f32_16x16x32_bf16 v[30:33], v[196:199], v[158:161], v[30:33]
	v_mfma_f32_16x16x32_bf16 v[26:29], v[204:207], v[158:161], v[26:29]
	v_mfma_f32_16x16x32_bf16 v[14:17], v[196:199], v[180:183], v[14:17]
	v_mfma_f32_16x16x32_bf16 v[10:13], v[204:207], v[180:183], v[10:13]
	v_mfma_f32_16x16x32_bf16 v[6:9], v[196:199], v[188:191], v[6:9]
	v_mfma_f32_16x16x32_bf16 v[2:5], v[204:207], v[188:191], v[2:5]
	s_add_u32 s0, s0, 0x100
	s_addc_u32 s1, s1, 0
	s_add_u32 s88, s88, 0x100
	s_addc_u32 s89, s89, 0
	s_cmp_ge_u32 s93, s26
	s_mov_b32 s22, s93
	s_barrier
	s_cbranch_scc0 .LBB0_745
	s_lshl_b32 s22, s75, 8
	s_lshl_b32 s0, s97, 8
	s_add_i32 s22, s22, s5
	s_or_b32 s75, s0, s72
	v_or_b32_e32 v176, s22, v1
	v_or_b32_e32 v178, s75, v216
	s_cmp_lt_i32 s77, 2
	s_mov_b64 s[0:1], -1
	s_cbranch_scc1 .LBB0_752
	s_cmp_gt_i32 s77, 2
	s_cbranch_scc0 .LBB0_749
	v_ashrrev_i32_e32 v179, 31, v178
	v_lshlrev_b64 v[180:181], 1, v[178:179]
	v_lshl_add_u64 v[180:181], s[46:47], 0, v[180:181]
	v_add_co_u32_e32 v180, vcc, 0xea000000, v180
	s_nop 1
	v_addc_co_u32_e32 v181, vcc, -1, v181, vcc
	v_lshlrev_b32_e32 v182, 2, v178
	v_readlane_b32 s98, v237, 62
	v_readlane_b32 s100, v238, 0
	v_readlane_b32 s101, v238, 1
	s_mul_i32 s98, s98, 0xab
	s_bfe_u32 s98, s98, 0x6000a
	s_mul_i32 s99, s98, 0x8400
	s_add_u32 s100, s100, s99
	s_addc_u32 s101, s101, 0
	s_nop 3
	global_load_dwordx4 v[130:133], v182, s[100:101] offset:0
	global_load_dwordx4 v[134:137], v182, s[100:101] offset:16
	s_add_u32 s100, s100, 0x2c00
	s_addc_u32 s101, s101, 0
	global_load_dwordx4 v[138:141], v182, s[100:101] offset:0
	global_load_dwordx4 v[142:145], v182, s[100:101] offset:16
	s_add_u32 s100, s100, 0x2c00
	s_addc_u32 s101, s101, 0
	global_load_dwordx4 v[146:149], v182, s[100:101] offset:0
	global_load_dwordx4 v[150:153], v182, s[100:101] offset:16
	v_readlane_b32 s100, v238, 2
	v_readlane_b32 s101, v238, 3
	s_mul_i32 s99, s98, 0x2c00
	s_add_u32 s100, s100, s99
	s_addc_u32 s101, s101, 0
	s_nop 3
	global_load_dwordx4 v[154:157], v182, s[100:101] offset:0
	global_load_dwordx4 v[158:161], v182, s[100:101] offset:16
	s_mov_b32 s98, 0x1600
	s_mov_b32 s99, 0
	s_mov_b32 s100, 0x16000000
	s_mov_b32 s101, 0
	v_add_u32_e32 v183, -1, v176
	v_mad_i64_i32 v[222:223], s[0:1], v183, s14, v[180:181]
	v_lshl_add_u64 v[224:225], v[222:223], 0, s[98:99]
	v_lshl_add_u64 v[226:227], v[224:225], 0, s[98:99]
	v_lshl_add_u64 v[196:197], v[224:225], 0, s[100:101]
	global_load_dwordx4 v[184:187], v[222:223], off
	global_load_dwordx4 v[188:191], v[224:225], off
	global_load_dwordx4 v[192:195], v[226:227], off
	v_add_u32_e32 v183, 0xf, v176
	v_mad_i64_i32 v[222:223], s[0:1], v183, s14, v[180:181]
	v_lshl_add_u64 v[224:225], v[222:223], 0, s[98:99]
	v_lshl_add_u64 v[226:227], v[224:225], 0, s[98:99]
	v_lshl_add_u64 v[220:221], v[224:225], 0, s[100:101]
	global_load_dwordx4 v[198:201], v[222:223], off
	global_load_dwordx4 v[202:205], v[224:225], off
	global_load_dwordx4 v[206:209], v[226:227], off
	s_waitcnt vmcnt(3)
; DI unsigned pack2(float a, float b) { f32x2_t v = {a, b}; bf16x2_t r = __builtin_convertvector(v, bf16x2_t); return __builtin_bit_cast(unsigned, r); }
; DI float lo2f(unsigned u) { return __uint_as_float(u << 16); }
; DI float hi2f(unsigned u) { return __uint_as_float(u & 0xffff0000u); }
;   DI void operator()(const f32x4 (&acc)[2][2][4][2], const pg8::Unit& u, int wr, int wc, int fr, int fq) const {
;     ...
;     } else {
; #pragma unroll
;       for (int ai = 0; ai < 2; ++ai) {
;         uint4 gs[4][2];
; #pragma unroll
;         for (int m = 0; m < 4; ++m)
; #pragma unroll
;           for (int bj = 0; bj < 2; ++bj)
;             gs[m][bj] = *(const uint4*)(o0 + (size_t)(row0 + ai * 128 + m * 16) * DFF + col0 + bj * 128);
;         __builtin_amdgcn_sched_barrier(0);
; #pragma unroll
;         for (int m = 0; m < 4; ++m)
; #pragma unroll
;           for (int bj = 0; bj < 2; ++bj) {
;             const f32x4 v0 = acc[ai][bj][m][0], v1 = acc[ai][bj][m][1];
;             const uint4 g = gs[m][bj];
;             f32x4 q0 = {lo2f(g.x) * v0[0], hi2f(g.x) * v0[1], lo2f(g.y) * v0[2], hi2f(g.y) * v0[3]};
;             f32x4 q1 = {lo2f(g.z) * v1[0], hi2f(g.z) * v1[1], lo2f(g.w) * v1[2], hi2f(g.w) * v1[3]};
;             st8(o0 + (size_t)(row0 + ai * 128 + m * 16) * DFF + col0 + bj * 128, q0, q1);
;           }
;         __builtin_amdgcn_sched_barrier(0);
;       }
; DI void conv_phase(const Params& p, int l) {
;     ...
;     rows[0] = (s0 > 0) ? *(const uint4*)(gp - DFF) : z;
; #pragma unroll
;     for (int i = 0; i < RUN; ++i) rows[i + 1] = *(const uint4*)(gp + (size_t)i * DFF);
;     rows[RUN + 1] = (s0 + RUN - 1 < S - 1) ? *(const uint4*)(gp + (size_t)RUN * DFF) : z;
;     float w0[8], w1[8], w2[8], bb[8];
;     load8f(cw + c0, w0); load8f(cw + DFF + c0, w1); load8f(cw + 2 * DFF + c0, w2); load8f(cb + c0, bb);
;     float prev[8], cur[8], nxt[8];
;     unpack8(rows[0], prev); unpack8(rows[1], cur);
; #pragma unroll
;     for (int i = 0; i < RUN; ++i) {
;       unpack8(rows[i + 2], nxt);
;       float o[8];
; #pragma unroll
;       for (int j = 0; j < 8; ++j) { const float g = w0[j] * prev[j] + w1[j] * cur[j] + w2[j] * nxt[j] + bb[j]; o[j] = g * sigmoidf_(g); }
;       uint4 oo; oo.x = pack2(o[0], o[1]); oo.y = pack2(o[2], o[3]); oo.z = pack2(o[4], o[5]); oo.w = pack2(o[6], o[7]);
;       *(uint4*)(GS + (size_t)(t0 + i) * DFF + c0) = oo;
	v_and_b32_e32 v183, 0x1fff, v176
	v_cmp_eq_u32_e32 vcc, 0, v183
	v_cndmask_b32_e64 v184, v184, 0, vcc
	v_cndmask_b32_e64 v185, v185, 0, vcc
	v_cndmask_b32_e64 v186, v186, 0, vcc
	v_cndmask_b32_e64 v187, v187, 0, vcc
	v_lshlrev_b32_e32 v240, 16, v184
	v_and_b32_e32 v241, 0xffff0000, v184
	v_lshlrev_b32_e32 v242, 16, v188
	v_and_b32_e32 v243, 0xffff0000, v188
	v_lshlrev_b32_e32 v252, 16, v192
	v_and_b32_e32 v253, 0xffff0000, v192
	v_fma_f32 v254, v130, v240, v154
	v_fma_f32 v255, v131, v241, v155
	v_fma_f32 v254, v138, v242, v254
	v_fma_f32 v255, v139, v243, v255
	v_fma_f32 v254, v146, v252, v254
	v_fma_f32 v255, v147, v253, v255
	v_mul_f32_e32 v240, 0xbfb8aa3b, v254
	v_mul_f32_e32 v241, 0xbfb8aa3b, v255
	v_exp_f32_e32 v240, v240
	v_exp_f32_e32 v241, v241
	v_add_f32_e32 v240, 1.0, v240
	v_add_f32_e32 v241, 1.0, v241
	v_rcp_f32_e32 v240, v240
	v_rcp_f32_e32 v241, v241
	v_mul_f32_e32 v254, v254, v240
	v_mul_f32_e32 v255, v255, v241
	v_mul_f32_e32 v254, v254, v126
	v_mul_f32_e32 v255, v255, v127
	v_cvt_pk_bf16_f32 v244, v254, v255
	v_lshlrev_b32_e32 v240, 16, v185
	v_and_b32_e32 v241, 0xffff0000, v185
	v_lshlrev_b32_e32 v242, 16, v189
	v_and_b32_e32 v243, 0xffff0000, v189
	v_lshlrev_b32_e32 v252, 16, v193
	v_and_b32_e32 v253, 0xffff0000, v193
	v_fma_f32 v254, v132, v240, v156
	v_fma_f32 v255, v133, v241, v157
	v_fma_f32 v254, v140, v242, v254
	v_fma_f32 v255, v141, v243, v255
	v_fma_f32 v254, v148, v252, v254
	v_fma_f32 v255, v149, v253, v255
	v_mul_f32_e32 v240, 0xbfb8aa3b, v254
	v_mul_f32_e32 v241, 0xbfb8aa3b, v255
	v_exp_f32_e32 v240, v240
	v_exp_f32_e32 v241, v241
	v_add_f32_e32 v240, 1.0, v240
	v_add_f32_e32 v241, 1.0, v241
	v_rcp_f32_e32 v240, v240
	v_rcp_f32_e32 v241, v241
	v_mul_f32_e32 v254, v254, v240
	v_mul_f32_e32 v255, v255, v241
	v_mul_f32_e32 v254, v254, v128
	v_mul_f32_e32 v255, v255, v129
	v_cvt_pk_bf16_f32 v245, v254, v255
	v_lshlrev_b32_e32 v240, 16, v186
	v_and_b32_e32 v241, 0xffff0000, v186
	v_lshlrev_b32_e32 v242, 16, v190
	v_and_b32_e32 v243, 0xffff0000, v190
	v_lshlrev_b32_e32 v252, 16, v194
	v_and_b32_e32 v253, 0xffff0000, v194
	v_fma_f32 v254, v134, v240, v158
	v_fma_f32 v255, v135, v241, v159
	v_fma_f32 v254, v142, v242, v254
	v_fma_f32 v255, v143, v243, v255
	v_fma_f32 v254, v150, v252, v254
	v_fma_f32 v255, v151, v253, v255
	v_mul_f32_e32 v240, 0xbfb8aa3b, v254
	v_mul_f32_e32 v241, 0xbfb8aa3b, v255
	v_exp_f32_e32 v240, v240
	v_exp_f32_e32 v241, v241
	v_add_f32_e32 v240, 1.0, v240
	v_add_f32_e32 v241, 1.0, v241
	v_rcp_f32_e32 v240, v240
	v_rcp_f32_e32 v241, v241
	v_mul_f32_e32 v254, v254, v240
	v_mul_f32_e32 v255, v255, v241
	v_mul_f32_e32 v254, v254, v122
	v_mul_f32_e32 v255, v255, v123
	v_cvt_pk_bf16_f32 v246, v254, v255
	v_lshlrev_b32_e32 v240, 16, v187
	v_and_b32_e32 v241, 0xffff0000, v187
	v_lshlrev_b32_e32 v242, 16, v191
	v_and_b32_e32 v243, 0xffff0000, v191
	v_lshlrev_b32_e32 v252, 16, v195
	v_and_b32_e32 v253, 0xffff0000, v195
	v_fma_f32 v254, v136, v240, v160
	v_fma_f32 v255, v137, v241, v161
	v_fma_f32 v254, v144, v242, v254
	v_fma_f32 v255, v145, v243, v255
	v_fma_f32 v254, v152, v252, v254
	v_fma_f32 v255, v153, v253, v255
	v_mul_f32_e32 v240, 0xbfb8aa3b, v254
	v_mul_f32_e32 v241, 0xbfb8aa3b, v255
	v_exp_f32_e32 v240, v240
	v_exp_f32_e32 v241, v241
	v_add_f32_e32 v240, 1.0, v240
	v_add_f32_e32 v241, 1.0, v241
	v_rcp_f32_e32 v240, v240
	v_rcp_f32_e32 v241, v241
	v_mul_f32_e32 v254, v254, v240
	v_mul_f32_e32 v255, v255, v241
	v_mul_f32_e32 v254, v254, v124
	v_mul_f32_e32 v255, v255, v125
	v_cvt_pk_bf16_f32 v247, v254, v255
	global_store_dwordx4 v[196:197], v[244:247], off
	v_add_u32_e32 v183, 0x1f, v176
	v_mad_i64_i32 v[222:223], s[0:1], v183, s14, v[180:181]
	v_lshl_add_u64 v[224:225], v[222:223], 0, s[98:99]
	v_lshl_add_u64 v[226:227], v[224:225], 0, s[98:99]
	v_lshl_add_u64 v[196:197], v[224:225], 0, s[100:101]
	global_load_dwordx4 v[184:187], v[222:223], off
	global_load_dwordx4 v[188:191], v[224:225], off
	global_load_dwordx4 v[192:195], v[226:227], off
	s_waitcnt vmcnt(4)
	v_lshlrev_b32_e32 v240, 16, v198
	v_and_b32_e32 v241, 0xffff0000, v198
	v_lshlrev_b32_e32 v242, 16, v202
	v_and_b32_e32 v243, 0xffff0000, v202
	v_lshlrev_b32_e32 v252, 16, v206
	v_and_b32_e32 v253, 0xffff0000, v206
	v_fma_f32 v254, v130, v240, v154
	v_fma_f32 v255, v131, v241, v155
	v_fma_f32 v254, v138, v242, v254
	v_fma_f32 v255, v139, v243, v255
	v_fma_f32 v254, v146, v252, v254
	v_fma_f32 v255, v147, v253, v255
	v_mul_f32_e32 v240, 0xbfb8aa3b, v254
	v_mul_f32_e32 v241, 0xbfb8aa3b, v255
	v_exp_f32_e32 v240, v240
	v_exp_f32_e32 v241, v241
	v_add_f32_e32 v240, 1.0, v240
	v_add_f32_e32 v241, 1.0, v241
	v_rcp_f32_e32 v240, v240
	v_rcp_f32_e32 v241, v241
	v_mul_f32_e32 v254, v254, v240
	v_mul_f32_e32 v255, v255, v241
	v_mul_f32_e32 v254, v254, v118
	v_mul_f32_e32 v255, v255, v119
	v_cvt_pk_bf16_f32 v248, v254, v255
	v_lshlrev_b32_e32 v240, 16, v199
	v_and_b32_e32 v241, 0xffff0000, v199
	v_lshlrev_b32_e32 v242, 16, v203
	v_and_b32_e32 v243, 0xffff0000, v203
	v_lshlrev_b32_e32 v252, 16, v207
	v_and_b32_e32 v253, 0xffff0000, v207
	v_fma_f32 v254, v132, v240, v156
	v_fma_f32 v255, v133, v241, v157
	v_fma_f32 v254, v140, v242, v254
	v_fma_f32 v255, v141, v243, v255
	v_fma_f32 v254, v148, v252, v254
	v_fma_f32 v255, v149, v253, v255
	v_mul_f32_e32 v240, 0xbfb8aa3b, v254
	v_mul_f32_e32 v241, 0xbfb8aa3b, v255
	v_exp_f32_e32 v240, v240
	v_exp_f32_e32 v241, v241
	v_add_f32_e32 v240, 1.0, v240
	v_add_f32_e32 v241, 1.0, v241
	v_rcp_f32_e32 v240, v240
	v_rcp_f32_e32 v241, v241
	v_mul_f32_e32 v254, v254, v240
	v_mul_f32_e32 v255, v255, v241
	v_mul_f32_e32 v254, v254, v120
	v_mul_f32_e32 v255, v255, v121
	v_cvt_pk_bf16_f32 v249, v254, v255
; DI unsigned pack2(float a, float b) { f32x2_t v = {a, b}; bf16x2_t r = __builtin_convertvector(v, bf16x2_t); return __builtin_bit_cast(unsigned, r); }
; DI float lo2f(unsigned u) { return __uint_as_float(u << 16); }
; DI float hi2f(unsigned u) { return __uint_as_float(u & 0xffff0000u); }
; DI float sigmoidf_(float x) { return __builtin_amdgcn_rcpf(1.f + __builtin_amdgcn_exp2f(-1.4426950408889634f * x)); }
;   DI void operator()(const f32x4 (&acc)[2][2][4][2], const pg8::Unit& u, int wr, int wc, int fr, int fq) const {
;     ...
;     } else {
; #pragma unroll
;       for (int ai = 0; ai < 2; ++ai) {
;         uint4 gs[4][2];
; #pragma unroll
;         for (int m = 0; m < 4; ++m)
; #pragma unroll
;           for (int bj = 0; bj < 2; ++bj)
;             gs[m][bj] = *(const uint4*)(o0 + (size_t)(row0 + ai * 128 + m * 16) * DFF + col0 + bj * 128);
;         __builtin_amdgcn_sched_barrier(0);
; #pragma unroll
;         for (int m = 0; m < 4; ++m)
; #pragma unroll
;           for (int bj = 0; bj < 2; ++bj) {
;             const f32x4 v0 = acc[ai][bj][m][0], v1 = acc[ai][bj][m][1];
;             const uint4 g = gs[m][bj];
;             f32x4 q0 = {lo2f(g.x) * v0[0], hi2f(g.x) * v0[1], lo2f(g.y) * v0[2], hi2f(g.y) * v0[3]};
;             f32x4 q1 = {lo2f(g.z) * v1[0], hi2f(g.z) * v1[1], lo2f(g.w) * v1[2], hi2f(g.w) * v1[3]};
;             st8(o0 + (size_t)(row0 + ai * 128 + m * 16) * DFF + col0 + bj * 128, q0, q1);
;           }
;         __builtin_amdgcn_sched_barrier(0);
;       }
; DI void conv_phase(const Params& p, int l) {
;     ...
;     for (int i = 0; i < RUN; ++i) {
;       unpack8(rows[i + 2], nxt);
;       float o[8];
; #pragma unroll
;       for (int j = 0; j < 8; ++j) { const float g = w0[j] * prev[j] + w1[j] * cur[j] + w2[j] * nxt[j] + bb[j]; o[j] = g * sigmoidf_(g); }
;       uint4 oo; oo.x = pack2(o[0], o[1]); oo.y = pack2(o[2], o[3]); oo.z = pack2(o[4], o[5]); oo.w = pack2(o[6], o[7]);
;       *(uint4*)(GS + (size_t)(t0 + i) * DFF + c0) = oo;
	v_lshlrev_b32_e32 v240, 16, v200
	v_and_b32_e32 v241, 0xffff0000, v200
	v_lshlrev_b32_e32 v242, 16, v204
	v_and_b32_e32 v243, 0xffff0000, v204
	v_lshlrev_b32_e32 v252, 16, v208
	v_and_b32_e32 v253, 0xffff0000, v208
	v_fma_f32 v254, v134, v240, v158
	v_fma_f32 v255, v135, v241, v159
	v_fma_f32 v254, v142, v242, v254
	v_fma_f32 v255, v143, v243, v255
	v_fma_f32 v254, v150, v252, v254
	v_fma_f32 v255, v151, v253, v255
	v_mul_f32_e32 v240, 0xbfb8aa3b, v254
	v_mul_f32_e32 v241, 0xbfb8aa3b, v255
	v_exp_f32_e32 v240, v240
	v_exp_f32_e32 v241, v241
	v_add_f32_e32 v240, 1.0, v240
	v_add_f32_e32 v241, 1.0, v241
	v_rcp_f32_e32 v240, v240
	v_rcp_f32_e32 v241, v241
	v_mul_f32_e32 v254, v254, v240
	v_mul_f32_e32 v255, v255, v241
	v_mul_f32_e32 v254, v254, v114
	v_mul_f32_e32 v255, v255, v115
	v_cvt_pk_bf16_f32 v250, v254, v255
	v_lshlrev_b32_e32 v240, 16, v201
	v_and_b32_e32 v241, 0xffff0000, v201
	v_lshlrev_b32_e32 v242, 16, v205
	v_and_b32_e32 v243, 0xffff0000, v205
	v_lshlrev_b32_e32 v252, 16, v209
	v_and_b32_e32 v253, 0xffff0000, v209
	v_fma_f32 v254, v136, v240, v160
	v_fma_f32 v255, v137, v241, v161
	v_fma_f32 v254, v144, v242, v254
	v_fma_f32 v255, v145, v243, v255
	v_fma_f32 v254, v152, v252, v254
	v_fma_f32 v255, v153, v253, v255
	v_mul_f32_e32 v240, 0xbfb8aa3b, v254
	v_mul_f32_e32 v241, 0xbfb8aa3b, v255
	v_exp_f32_e32 v240, v240
	v_exp_f32_e32 v241, v241
	v_add_f32_e32 v240, 1.0, v240
	v_add_f32_e32 v241, 1.0, v241
	v_rcp_f32_e32 v240, v240
	v_rcp_f32_e32 v241, v241
	v_mul_f32_e32 v254, v254, v240
	v_mul_f32_e32 v255, v255, v241
	v_mul_f32_e32 v254, v254, v116
	v_mul_f32_e32 v255, v255, v117
	v_cvt_pk_bf16_f32 v251, v254, v255
	global_store_dwordx4 v[220:221], v[248:251], off
	v_add_u32_e32 v183, 0x2f, v176
	v_mad_i64_i32 v[222:223], s[0:1], v183, s14, v[180:181]
	v_lshl_add_u64 v[224:225], v[222:223], 0, s[98:99]
	v_lshl_add_u64 v[226:227], v[224:225], 0, s[98:99]
	v_lshl_add_u64 v[220:221], v[224:225], 0, s[100:101]
	global_load_dwordx4 v[198:201], v[222:223], off
	global_load_dwordx4 v[202:205], v[224:225], off
	global_load_dwordx4 v[206:209], v[226:227], off
	s_waitcnt vmcnt(4)
	v_lshlrev_b32_e32 v240, 16, v184
	v_and_b32_e32 v241, 0xffff0000, v184
	v_lshlrev_b32_e32 v242, 16, v188
	v_and_b32_e32 v243, 0xffff0000, v188
	v_lshlrev_b32_e32 v252, 16, v192
	v_and_b32_e32 v253, 0xffff0000, v192
	v_fma_f32 v254, v130, v240, v154
	v_fma_f32 v255, v131, v241, v155
	v_fma_f32 v254, v138, v242, v254
	v_fma_f32 v255, v139, v243, v255
	v_fma_f32 v254, v146, v252, v254
	v_fma_f32 v255, v147, v253, v255
	v_mul_f32_e32 v240, 0xbfb8aa3b, v254
	v_mul_f32_e32 v241, 0xbfb8aa3b, v255
	v_exp_f32_e32 v240, v240
	v_exp_f32_e32 v241, v241
	v_add_f32_e32 v240, 1.0, v240
	v_add_f32_e32 v241, 1.0, v241
	v_rcp_f32_e32 v240, v240
	v_rcp_f32_e32 v241, v241
	v_mul_f32_e32 v254, v254, v240
	v_mul_f32_e32 v255, v255, v241
	v_mul_f32_e32 v254, v254, v102
	v_mul_f32_e32 v255, v255, v103
	v_cvt_pk_bf16_f32 v244, v254, v255
	v_lshlrev_b32_e32 v240, 16, v185
	v_and_b32_e32 v241, 0xffff0000, v185
	v_lshlrev_b32_e32 v242, 16, v189
	v_and_b32_e32 v243, 0xffff0000, v189
	v_lshlrev_b32_e32 v252, 16, v193
	v_and_b32_e32 v253, 0xffff0000, v193
	v_fma_f32 v254, v132, v240, v156
	v_fma_f32 v255, v133, v241, v157
	v_fma_f32 v254, v140, v242, v254
	v_fma_f32 v255, v141, v243, v255
	v_fma_f32 v254, v148, v252, v254
	v_fma_f32 v255, v149, v253, v255
	v_mul_f32_e32 v240, 0xbfb8aa3b, v254
	v_mul_f32_e32 v241, 0xbfb8aa3b, v255
	v_exp_f32_e32 v240, v240
	v_exp_f32_e32 v241, v241
	v_add_f32_e32 v240, 1.0, v240
	v_add_f32_e32 v241, 1.0, v241
	v_rcp_f32_e32 v240, v240
	v_rcp_f32_e32 v241, v241
	v_mul_f32_e32 v254, v254, v240
	v_mul_f32_e32 v255, v255, v241
	v_mul_f32_e32 v254, v254, v104
	v_mul_f32_e32 v255, v255, v105
	v_cvt_pk_bf16_f32 v245, v254, v255
	v_lshlrev_b32_e32 v240, 16, v186
	v_and_b32_e32 v241, 0xffff0000, v186
	v_lshlrev_b32_e32 v242, 16, v190
	v_and_b32_e32 v243, 0xffff0000, v190
	v_lshlrev_b32_e32 v252, 16, v194
	v_and_b32_e32 v253, 0xffff0000, v194
	v_fma_f32 v254, v134, v240, v158
	v_fma_f32 v255, v135, v241, v159
	v_fma_f32 v254, v142, v242, v254
	v_fma_f32 v255, v143, v243, v255
	v_fma_f32 v254, v150, v252, v254
	v_fma_f32 v255, v151, v253, v255
	v_mul_f32_e32 v240, 0xbfb8aa3b, v254
	v_mul_f32_e32 v241, 0xbfb8aa3b, v255
	v_exp_f32_e32 v240, v240
	v_exp_f32_e32 v241, v241
	v_add_f32_e32 v240, 1.0, v240
	v_add_f32_e32 v241, 1.0, v241
	v_rcp_f32_e32 v240, v240
	v_rcp_f32_e32 v241, v241
	v_mul_f32_e32 v254, v254, v240
	v_mul_f32_e32 v255, v255, v241
	v_mul_f32_e32 v254, v254, v98
	v_mul_f32_e32 v255, v255, v99
	v_cvt_pk_bf16_f32 v246, v254, v255
	v_lshlrev_b32_e32 v240, 16, v187
	v_and_b32_e32 v241, 0xffff0000, v187
	v_lshlrev_b32_e32 v242, 16, v191
	v_and_b32_e32 v243, 0xffff0000, v191
	v_lshlrev_b32_e32 v252, 16, v195
	v_and_b32_e32 v253, 0xffff0000, v195
	v_fma_f32 v254, v136, v240, v160
	v_fma_f32 v255, v137, v241, v161
	v_fma_f32 v254, v144, v242, v254
	v_fma_f32 v255, v145, v243, v255
	v_fma_f32 v254, v152, v252, v254
	v_fma_f32 v255, v153, v253, v255
	v_mul_f32_e32 v240, 0xbfb8aa3b, v254
	v_mul_f32_e32 v241, 0xbfb8aa3b, v255
	v_exp_f32_e32 v240, v240
	v_exp_f32_e32 v241, v241
	v_add_f32_e32 v240, 1.0, v240
	v_add_f32_e32 v241, 1.0, v241
	v_rcp_f32_e32 v240, v240
	v_rcp_f32_e32 v241, v241
	v_mul_f32_e32 v254, v254, v240
	v_mul_f32_e32 v255, v255, v241
	v_mul_f32_e32 v254, v254, v100
	v_mul_f32_e32 v255, v255, v101
	v_cvt_pk_bf16_f32 v247, v254, v255
	global_store_dwordx4 v[196:197], v[244:247], off
	v_add_u32_e32 v183, 0x7f, v176
	v_mad_i64_i32 v[222:223], s[0:1], v183, s14, v[180:181]
	v_lshl_add_u64 v[224:225], v[222:223], 0, s[98:99]
	v_lshl_add_u64 v[226:227], v[224:225], 0, s[98:99]
	v_lshl_add_u64 v[196:197], v[224:225], 0, s[100:101]
	global_load_dwordx4 v[184:187], v[222:223], off
	global_load_dwordx4 v[188:191], v[224:225], off
	global_load_dwordx4 v[192:195], v[226:227], off
	s_waitcnt vmcnt(4)
; DI unsigned pack2(float a, float b) { f32x2_t v = {a, b}; bf16x2_t r = __builtin_convertvector(v, bf16x2_t); return __builtin_bit_cast(unsigned, r); }
; DI float lo2f(unsigned u) { return __uint_as_float(u << 16); }
; DI float hi2f(unsigned u) { return __uint_as_float(u & 0xffff0000u); }
; DI float sigmoidf_(float x) { return __builtin_amdgcn_rcpf(1.f + __builtin_amdgcn_exp2f(-1.4426950408889634f * x)); }
;   DI void operator()(const f32x4 (&acc)[2][2][4][2], const pg8::Unit& u, int wr, int wc, int fr, int fq) const {
;     ...
;     } else {
; #pragma unroll
;       for (int ai = 0; ai < 2; ++ai) {
;         uint4 gs[4][2];
; #pragma unroll
;         for (int m = 0; m < 4; ++m)
; #pragma unroll
;           for (int bj = 0; bj < 2; ++bj)
;             gs[m][bj] = *(const uint4*)(o0 + (size_t)(row0 + ai * 128 + m * 16) * DFF + col0 + bj * 128);
;         __builtin_amdgcn_sched_barrier(0);
; #pragma unroll
;         for (int m = 0; m < 4; ++m)
; #pragma unroll
;           for (int bj = 0; bj < 2; ++bj) {
;             const f32x4 v0 = acc[ai][bj][m][0], v1 = acc[ai][bj][m][1];
;             const uint4 g = gs[m][bj];
;             f32x4 q0 = {lo2f(g.x) * v0[0], hi2f(g.x) * v0[1], lo2f(g.y) * v0[2], hi2f(g.y) * v0[3]};
;             f32x4 q1 = {lo2f(g.z) * v1[0], hi2f(g.z) * v1[1], lo2f(g.w) * v1[2], hi2f(g.w) * v1[3]};
;             st8(o0 + (size_t)(row0 + ai * 128 + m * 16) * DFF + col0 + bj * 128, q0, q1);
;           }
;         __builtin_amdgcn_sched_barrier(0);
;       }
; DI void conv_phase(const Params& p, int l) {
;     ...
;     for (int i = 0; i < RUN; ++i) {
;       unpack8(rows[i + 2], nxt);
;       float o[8];
; #pragma unroll
;       for (int j = 0; j < 8; ++j) { const float g = w0[j] * prev[j] + w1[j] * cur[j] + w2[j] * nxt[j] + bb[j]; o[j] = g * sigmoidf_(g); }
;       uint4 oo; oo.x = pack2(o[0], o[1]); oo.y = pack2(o[2], o[3]); oo.z = pack2(o[4], o[5]); oo.w = pack2(o[6], o[7]);
;       *(uint4*)(GS + (size_t)(t0 + i) * DFF + c0) = oo;
	v_lshlrev_b32_e32 v240, 16, v198
	v_and_b32_e32 v241, 0xffff0000, v198
	v_lshlrev_b32_e32 v242, 16, v202
	v_and_b32_e32 v243, 0xffff0000, v202
	v_lshlrev_b32_e32 v252, 16, v206
	v_and_b32_e32 v253, 0xffff0000, v206
	v_fma_f32 v254, v130, v240, v154
	v_fma_f32 v255, v131, v241, v155
	v_fma_f32 v254, v138, v242, v254
	v_fma_f32 v255, v139, v243, v255
	v_fma_f32 v254, v146, v252, v254
	v_fma_f32 v255, v147, v253, v255
	v_mul_f32_e32 v240, 0xbfb8aa3b, v254
	v_mul_f32_e32 v241, 0xbfb8aa3b, v255
	v_exp_f32_e32 v240, v240
	v_exp_f32_e32 v241, v241
	v_add_f32_e32 v240, 1.0, v240
	v_add_f32_e32 v241, 1.0, v241
	v_rcp_f32_e32 v240, v240
	v_rcp_f32_e32 v241, v241
	v_mul_f32_e32 v254, v254, v240
	v_mul_f32_e32 v255, v255, v241
	v_mul_f32_e32 v254, v254, v86
	v_mul_f32_e32 v255, v255, v87
	v_cvt_pk_bf16_f32 v248, v254, v255
	v_lshlrev_b32_e32 v240, 16, v199
	v_and_b32_e32 v241, 0xffff0000, v199
	v_lshlrev_b32_e32 v242, 16, v203
	v_and_b32_e32 v243, 0xffff0000, v203
	v_lshlrev_b32_e32 v252, 16, v207
	v_and_b32_e32 v253, 0xffff0000, v207
	v_fma_f32 v254, v132, v240, v156
	v_fma_f32 v255, v133, v241, v157
	v_fma_f32 v254, v140, v242, v254
	v_fma_f32 v255, v141, v243, v255
	v_fma_f32 v254, v148, v252, v254
	v_fma_f32 v255, v149, v253, v255
	v_mul_f32_e32 v240, 0xbfb8aa3b, v254
	v_mul_f32_e32 v241, 0xbfb8aa3b, v255
	v_exp_f32_e32 v240, v240
	v_exp_f32_e32 v241, v241
	v_add_f32_e32 v240, 1.0, v240
	v_add_f32_e32 v241, 1.0, v241
	v_rcp_f32_e32 v240, v240
	v_rcp_f32_e32 v241, v241
	v_mul_f32_e32 v254, v254, v240
	v_mul_f32_e32 v255, v255, v241
	v_mul_f32_e32 v254, v254, v88
	v_mul_f32_e32 v255, v255, v89
	v_cvt_pk_bf16_f32 v249, v254, v255
	v_lshlrev_b32_e32 v240, 16, v200
	v_and_b32_e32 v241, 0xffff0000, v200
	v_lshlrev_b32_e32 v242, 16, v204
	v_and_b32_e32 v243, 0xffff0000, v204
	v_lshlrev_b32_e32 v252, 16, v208
	v_and_b32_e32 v253, 0xffff0000, v208
	v_fma_f32 v254, v134, v240, v158
	v_fma_f32 v255, v135, v241, v159
	v_fma_f32 v254, v142, v242, v254
	v_fma_f32 v255, v143, v243, v255
	v_fma_f32 v254, v150, v252, v254
	v_fma_f32 v255, v151, v253, v255
	v_mul_f32_e32 v240, 0xbfb8aa3b, v254
	v_mul_f32_e32 v241, 0xbfb8aa3b, v255
	v_exp_f32_e32 v240, v240
	v_exp_f32_e32 v241, v241
	v_add_f32_e32 v240, 1.0, v240
	v_add_f32_e32 v241, 1.0, v241
	v_rcp_f32_e32 v240, v240
	v_rcp_f32_e32 v241, v241
	v_mul_f32_e32 v254, v254, v240
	v_mul_f32_e32 v255, v255, v241
	v_mul_f32_e32 v254, v254, v82
	v_mul_f32_e32 v255, v255, v83
	v_cvt_pk_bf16_f32 v250, v254, v255
	v_lshlrev_b32_e32 v240, 16, v201
	v_and_b32_e32 v241, 0xffff0000, v201
	v_lshlrev_b32_e32 v242, 16, v205
	v_and_b32_e32 v243, 0xffff0000, v205
	v_lshlrev_b32_e32 v252, 16, v209
	v_and_b32_e32 v253, 0xffff0000, v209
	v_fma_f32 v254, v136, v240, v160
	v_fma_f32 v255, v137, v241, v161
	v_fma_f32 v254, v144, v242, v254
	v_fma_f32 v255, v145, v243, v255
	v_fma_f32 v254, v152, v252, v254
	v_fma_f32 v255, v153, v253, v255
	v_mul_f32_e32 v240, 0xbfb8aa3b, v254
	v_mul_f32_e32 v241, 0xbfb8aa3b, v255
	v_exp_f32_e32 v240, v240
	v_exp_f32_e32 v241, v241
	v_add_f32_e32 v240, 1.0, v240
	v_add_f32_e32 v241, 1.0, v241
	v_rcp_f32_e32 v240, v240
	v_rcp_f32_e32 v241, v241
	v_mul_f32_e32 v254, v254, v240
	v_mul_f32_e32 v255, v255, v241
	v_mul_f32_e32 v254, v254, v84
	v_mul_f32_e32 v255, v255, v85
	v_cvt_pk_bf16_f32 v251, v254, v255
	global_store_dwordx4 v[220:221], v[248:251], off
	v_add_u32_e32 v183, 0x8f, v176
	v_mad_i64_i32 v[222:223], s[0:1], v183, s14, v[180:181]
	v_lshl_add_u64 v[224:225], v[222:223], 0, s[98:99]
	v_lshl_add_u64 v[226:227], v[224:225], 0, s[98:99]
	v_lshl_add_u64 v[220:221], v[224:225], 0, s[100:101]
	global_load_dwordx4 v[198:201], v[222:223], off
	global_load_dwordx4 v[202:205], v[224:225], off
	global_load_dwordx4 v[206:209], v[226:227], off
	s_waitcnt vmcnt(4)
	v_lshlrev_b32_e32 v240, 16, v184
	v_and_b32_e32 v241, 0xffff0000, v184
	v_lshlrev_b32_e32 v242, 16, v188
	v_and_b32_e32 v243, 0xffff0000, v188
	v_lshlrev_b32_e32 v252, 16, v192
	v_and_b32_e32 v253, 0xffff0000, v192
	v_fma_f32 v254, v130, v240, v154
	v_fma_f32 v255, v131, v241, v155
	v_fma_f32 v254, v138, v242, v254
	v_fma_f32 v255, v139, v243, v255
	v_fma_f32 v254, v146, v252, v254
	v_fma_f32 v255, v147, v253, v255
	v_mul_f32_e32 v240, 0xbfb8aa3b, v254
	v_mul_f32_e32 v241, 0xbfb8aa3b, v255
	v_exp_f32_e32 v240, v240
	v_exp_f32_e32 v241, v241
	v_add_f32_e32 v240, 1.0, v240
	v_add_f32_e32 v241, 1.0, v241
	v_rcp_f32_e32 v240, v240
	v_rcp_f32_e32 v241, v241
	v_mul_f32_e32 v254, v254, v240
	v_mul_f32_e32 v255, v255, v241
	v_mul_f32_e32 v254, v254, v62
	v_mul_f32_e32 v255, v255, v63
	v_cvt_pk_bf16_f32 v244, v254, v255
	v_lshlrev_b32_e32 v240, 16, v185
	v_and_b32_e32 v241, 0xffff0000, v185
	v_lshlrev_b32_e32 v242, 16, v189
	v_and_b32_e32 v243, 0xffff0000, v189
	v_lshlrev_b32_e32 v252, 16, v193
	v_and_b32_e32 v253, 0xffff0000, v193
	v_fma_f32 v254, v132, v240, v156
	v_fma_f32 v255, v133, v241, v157
	v_fma_f32 v254, v140, v242, v254
	v_fma_f32 v255, v141, v243, v255
	v_fma_f32 v254, v148, v252, v254
	v_fma_f32 v255, v149, v253, v255
	v_mul_f32_e32 v240, 0xbfb8aa3b, v254
	v_mul_f32_e32 v241, 0xbfb8aa3b, v255
	v_exp_f32_e32 v240, v240
	v_exp_f32_e32 v241, v241
	v_add_f32_e32 v240, 1.0, v240
	v_add_f32_e32 v241, 1.0, v241
	v_rcp_f32_e32 v240, v240
	v_rcp_f32_e32 v241, v241
	v_mul_f32_e32 v254, v254, v240
	v_mul_f32_e32 v255, v255, v241
	v_mul_f32_e32 v254, v254, v64
	v_mul_f32_e32 v255, v255, v65
	v_cvt_pk_bf16_f32 v245, v254, v255
	v_lshlrev_b32_e32 v240, 16, v186
	v_and_b32_e32 v241, 0xffff0000, v186
	v_lshlrev_b32_e32 v242, 16, v190
	v_and_b32_e32 v243, 0xffff0000, v190
	v_lshlrev_b32_e32 v252, 16, v194
	v_and_b32_e32 v253, 0xffff0000, v194
; DI unsigned pack2(float a, float b) { f32x2_t v = {a, b}; bf16x2_t r = __builtin_convertvector(v, bf16x2_t); return __builtin_bit_cast(unsigned, r); }
; DI float lo2f(unsigned u) { return __uint_as_float(u << 16); }
; DI float hi2f(unsigned u) { return __uint_as_float(u & 0xffff0000u); }
; DI float sigmoidf_(float x) { return __builtin_amdgcn_rcpf(1.f + __builtin_amdgcn_exp2f(-1.4426950408889634f * x)); }
;   DI void operator()(const f32x4 (&acc)[2][2][4][2], const pg8::Unit& u, int wr, int wc, int fr, int fq) const {
;     ...
;     } else {
; #pragma unroll
;       for (int ai = 0; ai < 2; ++ai) {
;         uint4 gs[4][2];
; #pragma unroll
;         for (int m = 0; m < 4; ++m)
; #pragma unroll
;           for (int bj = 0; bj < 2; ++bj)
;             gs[m][bj] = *(const uint4*)(o0 + (size_t)(row0 + ai * 128 + m * 16) * DFF + col0 + bj * 128);
;         __builtin_amdgcn_sched_barrier(0);
; #pragma unroll
;         for (int m = 0; m < 4; ++m)
; #pragma unroll
;           for (int bj = 0; bj < 2; ++bj) {
;             const f32x4 v0 = acc[ai][bj][m][0], v1 = acc[ai][bj][m][1];
;             const uint4 g = gs[m][bj];
;             f32x4 q0 = {lo2f(g.x) * v0[0], hi2f(g.x) * v0[1], lo2f(g.y) * v0[2], hi2f(g.y) * v0[3]};
;             f32x4 q1 = {lo2f(g.z) * v1[0], hi2f(g.z) * v1[1], lo2f(g.w) * v1[2], hi2f(g.w) * v1[3]};
;             st8(o0 + (size_t)(row0 + ai * 128 + m * 16) * DFF + col0 + bj * 128, q0, q1);
;           }
;         __builtin_amdgcn_sched_barrier(0);
;       }
; DI void conv_phase(const Params& p, int l) {
;     ...
;     for (int i = 0; i < RUN; ++i) {
;       unpack8(rows[i + 2], nxt);
;       float o[8];
; #pragma unroll
;       for (int j = 0; j < 8; ++j) { const float g = w0[j] * prev[j] + w1[j] * cur[j] + w2[j] * nxt[j] + bb[j]; o[j] = g * sigmoidf_(g); }
;       uint4 oo; oo.x = pack2(o[0], o[1]); oo.y = pack2(o[2], o[3]); oo.z = pack2(o[4], o[5]); oo.w = pack2(o[6], o[7]);
;       *(uint4*)(GS + (size_t)(t0 + i) * DFF + c0) = oo;
	v_fma_f32 v254, v134, v240, v158
	v_fma_f32 v255, v135, v241, v159
	v_fma_f32 v254, v142, v242, v254
	v_fma_f32 v255, v143, v243, v255
	v_fma_f32 v254, v150, v252, v254
	v_fma_f32 v255, v151, v253, v255
	v_mul_f32_e32 v240, 0xbfb8aa3b, v254
	v_mul_f32_e32 v241, 0xbfb8aa3b, v255
	v_exp_f32_e32 v240, v240
	v_exp_f32_e32 v241, v241
	v_add_f32_e32 v240, 1.0, v240
	v_add_f32_e32 v241, 1.0, v241
	v_rcp_f32_e32 v240, v240
	v_rcp_f32_e32 v241, v241
	v_mul_f32_e32 v254, v254, v240
	v_mul_f32_e32 v255, v255, v241
	v_mul_f32_e32 v254, v254, v58
	v_mul_f32_e32 v255, v255, v59
	v_cvt_pk_bf16_f32 v246, v254, v255
	v_lshlrev_b32_e32 v240, 16, v187
	v_and_b32_e32 v241, 0xffff0000, v187
	v_lshlrev_b32_e32 v242, 16, v191
	v_and_b32_e32 v243, 0xffff0000, v191
	v_lshlrev_b32_e32 v252, 16, v195
	v_and_b32_e32 v253, 0xffff0000, v195
	v_fma_f32 v254, v136, v240, v160
	v_fma_f32 v255, v137, v241, v161
	v_fma_f32 v254, v144, v242, v254
	v_fma_f32 v255, v145, v243, v255
	v_fma_f32 v254, v152, v252, v254
	v_fma_f32 v255, v153, v253, v255
	v_mul_f32_e32 v240, 0xbfb8aa3b, v254
	v_mul_f32_e32 v241, 0xbfb8aa3b, v255
	v_exp_f32_e32 v240, v240
	v_exp_f32_e32 v241, v241
	v_add_f32_e32 v240, 1.0, v240
	v_add_f32_e32 v241, 1.0, v241
	v_rcp_f32_e32 v240, v240
	v_rcp_f32_e32 v241, v241
	v_mul_f32_e32 v254, v254, v240
	v_mul_f32_e32 v255, v255, v241
	v_mul_f32_e32 v254, v254, v60
	v_mul_f32_e32 v255, v255, v61
	v_cvt_pk_bf16_f32 v247, v254, v255
	global_store_dwordx4 v[196:197], v[244:247], off
	v_add_u32_e32 v183, 0x9f, v176
	v_mad_i64_i32 v[222:223], s[0:1], v183, s14, v[180:181]
	v_lshl_add_u64 v[224:225], v[222:223], 0, s[98:99]
	v_lshl_add_u64 v[226:227], v[224:225], 0, s[98:99]
	v_lshl_add_u64 v[196:197], v[224:225], 0, s[100:101]
	global_load_dwordx4 v[184:187], v[222:223], off
	global_load_dwordx4 v[188:191], v[224:225], off
	global_load_dwordx4 v[192:195], v[226:227], off
	s_waitcnt vmcnt(4)
	v_lshlrev_b32_e32 v240, 16, v198
	v_and_b32_e32 v241, 0xffff0000, v198
	v_lshlrev_b32_e32 v242, 16, v202
	v_and_b32_e32 v243, 0xffff0000, v202
	v_lshlrev_b32_e32 v252, 16, v206
	v_and_b32_e32 v253, 0xffff0000, v206
	v_fma_f32 v254, v130, v240, v154
	v_fma_f32 v255, v131, v241, v155
	v_fma_f32 v254, v138, v242, v254
	v_fma_f32 v255, v139, v243, v255
	v_fma_f32 v254, v146, v252, v254
	v_fma_f32 v255, v147, v253, v255
	v_mul_f32_e32 v240, 0xbfb8aa3b, v254
	v_mul_f32_e32 v241, 0xbfb8aa3b, v255
	v_exp_f32_e32 v240, v240
	v_exp_f32_e32 v241, v241
	v_add_f32_e32 v240, 1.0, v240
	v_add_f32_e32 v241, 1.0, v241
	v_rcp_f32_e32 v240, v240
	v_rcp_f32_e32 v241, v241
	v_mul_f32_e32 v254, v254, v240
	v_mul_f32_e32 v255, v255, v241
	v_mul_f32_e32 v254, v254, v54
	v_mul_f32_e32 v255, v255, v55
	v_cvt_pk_bf16_f32 v248, v254, v255
	v_lshlrev_b32_e32 v240, 16, v199
	v_and_b32_e32 v241, 0xffff0000, v199
	v_lshlrev_b32_e32 v242, 16, v203
	v_and_b32_e32 v243, 0xffff0000, v203
	v_lshlrev_b32_e32 v252, 16, v207
	v_and_b32_e32 v253, 0xffff0000, v207
	v_fma_f32 v254, v132, v240, v156
	v_fma_f32 v255, v133, v241, v157
	v_fma_f32 v254, v140, v242, v254
	v_fma_f32 v255, v141, v243, v255
	v_fma_f32 v254, v148, v252, v254
	v_fma_f32 v255, v149, v253, v255
	v_mul_f32_e32 v240, 0xbfb8aa3b, v254
	v_mul_f32_e32 v241, 0xbfb8aa3b, v255
	v_exp_f32_e32 v240, v240
	v_exp_f32_e32 v241, v241
	v_add_f32_e32 v240, 1.0, v240
	v_add_f32_e32 v241, 1.0, v241
	v_rcp_f32_e32 v240, v240
	v_rcp_f32_e32 v241, v241
	v_mul_f32_e32 v254, v254, v240
	v_mul_f32_e32 v255, v255, v241
	v_mul_f32_e32 v254, v254, v56
	v_mul_f32_e32 v255, v255, v57
	v_cvt_pk_bf16_f32 v249, v254, v255
	v_lshlrev_b32_e32 v240, 16, v200
	v_and_b32_e32 v241, 0xffff0000, v200
	v_lshlrev_b32_e32 v242, 16, v204
	v_and_b32_e32 v243, 0xffff0000, v204
	v_lshlrev_b32_e32 v252, 16, v208
	v_and_b32_e32 v253, 0xffff0000, v208
	v_fma_f32 v254, v134, v240, v158
	v_fma_f32 v255, v135, v241, v159
	v_fma_f32 v254, v142, v242, v254
	v_fma_f32 v255, v143, v243, v255
	v_fma_f32 v254, v150, v252, v254
	v_fma_f32 v255, v151, v253, v255
	v_mul_f32_e32 v240, 0xbfb8aa3b, v254
	v_mul_f32_e32 v241, 0xbfb8aa3b, v255
	v_exp_f32_e32 v240, v240
	v_exp_f32_e32 v241, v241
	v_add_f32_e32 v240, 1.0, v240
	v_add_f32_e32 v241, 1.0, v241
	v_rcp_f32_e32 v240, v240
	v_rcp_f32_e32 v241, v241
	v_mul_f32_e32 v254, v254, v240
	v_mul_f32_e32 v255, v255, v241
	v_mul_f32_e32 v254, v254, v50
	v_mul_f32_e32 v255, v255, v51
	v_cvt_pk_bf16_f32 v250, v254, v255
	v_lshlrev_b32_e32 v240, 16, v201
	v_and_b32_e32 v241, 0xffff0000, v201
	v_lshlrev_b32_e32 v242, 16, v205
	v_and_b32_e32 v243, 0xffff0000, v205
	v_lshlrev_b32_e32 v252, 16, v209
	v_and_b32_e32 v253, 0xffff0000, v209
	v_fma_f32 v254, v136, v240, v160
	v_fma_f32 v255, v137, v241, v161
	v_fma_f32 v254, v144, v242, v254
	v_fma_f32 v255, v145, v243, v255
	v_fma_f32 v254, v152, v252, v254
	v_fma_f32 v255, v153, v253, v255
	v_mul_f32_e32 v240, 0xbfb8aa3b, v254
	v_mul_f32_e32 v241, 0xbfb8aa3b, v255
	v_exp_f32_e32 v240, v240
	v_exp_f32_e32 v241, v241
	v_add_f32_e32 v240, 1.0, v240
	v_add_f32_e32 v241, 1.0, v241
	v_rcp_f32_e32 v240, v240
	v_rcp_f32_e32 v241, v241
	v_mul_f32_e32 v254, v254, v240
	v_mul_f32_e32 v255, v255, v241
	v_mul_f32_e32 v254, v254, v52
	v_mul_f32_e32 v255, v255, v53
	v_cvt_pk_bf16_f32 v251, v254, v255
	global_store_dwordx4 v[220:221], v[248:251], off
	v_add_u32_e32 v183, 0xaf, v176
	v_mad_i64_i32 v[222:223], s[0:1], v183, s14, v[180:181]
	v_lshl_add_u64 v[224:225], v[222:223], 0, s[98:99]
	v_lshl_add_u64 v[226:227], v[224:225], 0, s[98:99]
	v_lshl_add_u64 v[220:221], v[224:225], 0, s[100:101]
	global_load_dwordx4 v[198:201], v[222:223], off
	global_load_dwordx4 v[202:205], v[224:225], off
	global_load_dwordx4 v[206:209], v[226:227], off
	s_waitcnt vmcnt(4)
; DI unsigned pack2(float a, float b) { f32x2_t v = {a, b}; bf16x2_t r = __builtin_convertvector(v, bf16x2_t); return __builtin_bit_cast(unsigned, r); }
; DI float lo2f(unsigned u) { return __uint_as_float(u << 16); }
; DI float hi2f(unsigned u) { return __uint_as_float(u & 0xffff0000u); }
; DI float sigmoidf_(float x) { return __builtin_amdgcn_rcpf(1.f + __builtin_amdgcn_exp2f(-1.4426950408889634f * x)); }
;   DI void operator()(const f32x4 (&acc)[2][2][4][2], const pg8::Unit& u, int wr, int wc, int fr, int fq) const {
;     ...
;     } else {
; #pragma unroll
;       for (int ai = 0; ai < 2; ++ai) {
;         uint4 gs[4][2];
; #pragma unroll
;         for (int m = 0; m < 4; ++m)
; #pragma unroll
;           for (int bj = 0; bj < 2; ++bj)
;             gs[m][bj] = *(const uint4*)(o0 + (size_t)(row0 + ai * 128 + m * 16) * DFF + col0 + bj * 128);
;         __builtin_amdgcn_sched_barrier(0);
; #pragma unroll
;         for (int m = 0; m < 4; ++m)
; #pragma unroll
;           for (int bj = 0; bj < 2; ++bj) {
;             const f32x4 v0 = acc[ai][bj][m][0], v1 = acc[ai][bj][m][1];
;             const uint4 g = gs[m][bj];
;             f32x4 q0 = {lo2f(g.x) * v0[0], hi2f(g.x) * v0[1], lo2f(g.y) * v0[2], hi2f(g.y) * v0[3]};
;             f32x4 q1 = {lo2f(g.z) * v1[0], hi2f(g.z) * v1[1], lo2f(g.w) * v1[2], hi2f(g.w) * v1[3]};
;             st8(o0 + (size_t)(row0 + ai * 128 + m * 16) * DFF + col0 + bj * 128, q0, q1);
;           }
;         __builtin_amdgcn_sched_barrier(0);
;       }
; DI void conv_phase(const Params& p, int l) {
;     ...
;     rows[RUN + 1] = (s0 + RUN - 1 < S - 1) ? *(const uint4*)(gp + (size_t)RUN * DFF) : z;
;     float w0[8], w1[8], w2[8], bb[8];
;     load8f(cw + c0, w0); load8f(cw + DFF + c0, w1); load8f(cw + 2 * DFF + c0, w2); load8f(cb + c0, bb);
;     float prev[8], cur[8], nxt[8];
;     unpack8(rows[0], prev); unpack8(rows[1], cur);
; #pragma unroll
;     for (int i = 0; i < RUN; ++i) {
;       unpack8(rows[i + 2], nxt);
;       float o[8];
; #pragma unroll
;       for (int j = 0; j < 8; ++j) { const float g = w0[j] * prev[j] + w1[j] * cur[j] + w2[j] * nxt[j] + bb[j]; o[j] = g * sigmoidf_(g); }
;       uint4 oo; oo.x = pack2(o[0], o[1]); oo.y = pack2(o[2], o[3]); oo.z = pack2(o[4], o[5]); oo.w = pack2(o[6], o[7]);
;       *(uint4*)(GS + (size_t)(t0 + i) * DFF + c0) = oo;
	v_lshlrev_b32_e32 v240, 16, v184
	v_and_b32_e32 v241, 0xffff0000, v184
	v_lshlrev_b32_e32 v242, 16, v188
	v_and_b32_e32 v243, 0xffff0000, v188
	v_lshlrev_b32_e32 v252, 16, v192
	v_and_b32_e32 v253, 0xffff0000, v192
	v_fma_f32 v254, v130, v240, v154
	v_fma_f32 v255, v131, v241, v155
	v_fma_f32 v254, v138, v242, v254
	v_fma_f32 v255, v139, v243, v255
	v_fma_f32 v254, v146, v252, v254
	v_fma_f32 v255, v147, v253, v255
	v_mul_f32_e32 v240, 0xbfb8aa3b, v254
	v_mul_f32_e32 v241, 0xbfb8aa3b, v255
	v_exp_f32_e32 v240, v240
	v_exp_f32_e32 v241, v241
	v_add_f32_e32 v240, 1.0, v240
	v_add_f32_e32 v241, 1.0, v241
	v_rcp_f32_e32 v240, v240
	v_rcp_f32_e32 v241, v241
	v_mul_f32_e32 v254, v254, v240
	v_mul_f32_e32 v255, v255, v241
	v_mul_f32_e32 v254, v254, v38
	v_mul_f32_e32 v255, v255, v39
	v_cvt_pk_bf16_f32 v244, v254, v255
	v_lshlrev_b32_e32 v240, 16, v185
	v_and_b32_e32 v241, 0xffff0000, v185
	v_lshlrev_b32_e32 v242, 16, v189
	v_and_b32_e32 v243, 0xffff0000, v189
	v_lshlrev_b32_e32 v252, 16, v193
	v_and_b32_e32 v253, 0xffff0000, v193
	v_fma_f32 v254, v132, v240, v156
	v_fma_f32 v255, v133, v241, v157
	v_fma_f32 v254, v140, v242, v254
	v_fma_f32 v255, v141, v243, v255
	v_fma_f32 v254, v148, v252, v254
	v_fma_f32 v255, v149, v253, v255
	v_mul_f32_e32 v240, 0xbfb8aa3b, v254
	v_mul_f32_e32 v241, 0xbfb8aa3b, v255
	v_exp_f32_e32 v240, v240
	v_exp_f32_e32 v241, v241
	v_add_f32_e32 v240, 1.0, v240
	v_add_f32_e32 v241, 1.0, v241
	v_rcp_f32_e32 v240, v240
	v_rcp_f32_e32 v241, v241
	v_mul_f32_e32 v254, v254, v240
	v_mul_f32_e32 v255, v255, v241
	v_mul_f32_e32 v254, v254, v40
	v_mul_f32_e32 v255, v255, v41
	v_cvt_pk_bf16_f32 v245, v254, v255
	v_lshlrev_b32_e32 v240, 16, v186
	v_and_b32_e32 v241, 0xffff0000, v186
	v_lshlrev_b32_e32 v242, 16, v190
	v_and_b32_e32 v243, 0xffff0000, v190
	v_lshlrev_b32_e32 v252, 16, v194
	v_and_b32_e32 v253, 0xffff0000, v194
	v_fma_f32 v254, v134, v240, v158
	v_fma_f32 v255, v135, v241, v159
	v_fma_f32 v254, v142, v242, v254
	v_fma_f32 v255, v143, v243, v255
	v_fma_f32 v254, v150, v252, v254
	v_fma_f32 v255, v151, v253, v255
	v_mul_f32_e32 v240, 0xbfb8aa3b, v254
	v_mul_f32_e32 v241, 0xbfb8aa3b, v255
	v_exp_f32_e32 v240, v240
	v_exp_f32_e32 v241, v241
	v_add_f32_e32 v240, 1.0, v240
	v_add_f32_e32 v241, 1.0, v241
	v_rcp_f32_e32 v240, v240
	v_rcp_f32_e32 v241, v241
	v_mul_f32_e32 v254, v254, v240
	v_mul_f32_e32 v255, v255, v241
	v_mul_f32_e32 v254, v254, v34
	v_mul_f32_e32 v255, v255, v35
	v_cvt_pk_bf16_f32 v246, v254, v255
	v_lshlrev_b32_e32 v240, 16, v187
	v_and_b32_e32 v241, 0xffff0000, v187
	v_lshlrev_b32_e32 v242, 16, v191
	v_and_b32_e32 v243, 0xffff0000, v191
	v_lshlrev_b32_e32 v252, 16, v195
	v_and_b32_e32 v253, 0xffff0000, v195
	v_fma_f32 v254, v136, v240, v160
	v_fma_f32 v255, v137, v241, v161
	v_fma_f32 v254, v144, v242, v254
	v_fma_f32 v255, v145, v243, v255
	v_fma_f32 v254, v152, v252, v254
	v_fma_f32 v255, v153, v253, v255
	v_mul_f32_e32 v240, 0xbfb8aa3b, v254
	v_mul_f32_e32 v241, 0xbfb8aa3b, v255
	v_exp_f32_e32 v240, v240
	v_exp_f32_e32 v241, v241
	v_add_f32_e32 v240, 1.0, v240
	v_add_f32_e32 v241, 1.0, v241
	v_rcp_f32_e32 v240, v240
	v_rcp_f32_e32 v241, v241
	v_mul_f32_e32 v254, v254, v240
	v_mul_f32_e32 v255, v255, v241
	v_mul_f32_e32 v254, v254, v36
	v_mul_f32_e32 v255, v255, v37
	v_cvt_pk_bf16_f32 v247, v254, v255
	global_store_dwordx4 v[196:197], v[244:247], off
	s_waitcnt vmcnt(1)
	v_add_u32_e32 v183, 0xb0, v176
	v_and_b32_e32 v183, 0x1fff, v183
	v_cmp_eq_u32_e32 vcc, 0x1fff, v183
	v_cndmask_b32_e64 v206, v206, 0, vcc
	v_cndmask_b32_e64 v207, v207, 0, vcc
	v_cndmask_b32_e64 v208, v208, 0, vcc
	v_cndmask_b32_e64 v209, v209, 0, vcc
	v_lshlrev_b32_e32 v240, 16, v198
	v_and_b32_e32 v241, 0xffff0000, v198
	v_lshlrev_b32_e32 v242, 16, v202
	v_and_b32_e32 v243, 0xffff0000, v202
	v_lshlrev_b32_e32 v252, 16, v206
	v_and_b32_e32 v253, 0xffff0000, v206
	v_fma_f32 v254, v130, v240, v154
	v_fma_f32 v255, v131, v241, v155
	v_fma_f32 v254, v138, v242, v254
	v_fma_f32 v255, v139, v243, v255
	v_fma_f32 v254, v146, v252, v254
	v_fma_f32 v255, v147, v253, v255
	v_mul_f32_e32 v240, 0xbfb8aa3b, v254
	v_mul_f32_e32 v241, 0xbfb8aa3b, v255
	v_exp_f32_e32 v240, v240
	v_exp_f32_e32 v241, v241
	v_add_f32_e32 v240, 1.0, v240
	v_add_f32_e32 v241, 1.0, v241
	v_rcp_f32_e32 v240, v240
	v_rcp_f32_e32 v241, v241
	v_mul_f32_e32 v254, v254, v240
	v_mul_f32_e32 v255, v255, v241
	v_mul_f32_e32 v254, v254, v22
	v_mul_f32_e32 v255, v255, v23
	v_cvt_pk_bf16_f32 v248, v254, v255
	v_lshlrev_b32_e32 v240, 16, v199
	v_and_b32_e32 v241, 0xffff0000, v199
	v_lshlrev_b32_e32 v242, 16, v203
	v_and_b32_e32 v243, 0xffff0000, v203
	v_lshlrev_b32_e32 v252, 16, v207
	v_and_b32_e32 v253, 0xffff0000, v207
	v_fma_f32 v254, v132, v240, v156
	v_fma_f32 v255, v133, v241, v157
	v_fma_f32 v254, v140, v242, v254
	v_fma_f32 v255, v141, v243, v255
	v_fma_f32 v254, v148, v252, v254
	v_fma_f32 v255, v149, v253, v255
	v_mul_f32_e32 v240, 0xbfb8aa3b, v254
	v_mul_f32_e32 v241, 0xbfb8aa3b, v255
	v_exp_f32_e32 v240, v240
	v_exp_f32_e32 v241, v241
	v_add_f32_e32 v240, 1.0, v240
	v_add_f32_e32 v241, 1.0, v241
	v_rcp_f32_e32 v240, v240
	v_rcp_f32_e32 v241, v241
	v_mul_f32_e32 v254, v254, v240
	v_mul_f32_e32 v255, v255, v241
	v_mul_f32_e32 v254, v254, v24
	v_mul_f32_e32 v255, v255, v25
	v_cvt_pk_bf16_f32 v249, v254, v255
	v_lshlrev_b32_e32 v240, 16, v200
	v_and_b32_e32 v241, 0xffff0000, v200
	v_lshlrev_b32_e32 v242, 16, v204
	v_and_b32_e32 v243, 0xffff0000, v204
	v_lshlrev_b32_e32 v252, 16, v208
	v_and_b32_e32 v253, 0xffff0000, v208
	v_fma_f32 v254, v134, v240, v158
	v_fma_f32 v255, v135, v241, v159
	v_fma_f32 v254, v142, v242, v254
	v_fma_f32 v255, v143, v243, v255
	v_fma_f32 v254, v150, v252, v254
; DI unsigned pack2(float a, float b) { f32x2_t v = {a, b}; bf16x2_t r = __builtin_convertvector(v, bf16x2_t); return __builtin_bit_cast(unsigned, r); }
; DI float lo2f(unsigned u) { return __uint_as_float(u << 16); }
; DI float hi2f(unsigned u) { return __uint_as_float(u & 0xffff0000u); }
; DI float sigmoidf_(float x) { return __builtin_amdgcn_rcpf(1.f + __builtin_amdgcn_exp2f(-1.4426950408889634f * x)); }
;   DI void operator()(const f32x4 (&acc)[2][2][4][2], const pg8::Unit& u, int wr, int wc, int fr, int fq) const {
;     ...
;     } else {
; #pragma unroll
;       for (int ai = 0; ai < 2; ++ai) {
;         uint4 gs[4][2];
; #pragma unroll
;         for (int m = 0; m < 4; ++m)
; #pragma unroll
;           for (int bj = 0; bj < 2; ++bj)
;             gs[m][bj] = *(const uint4*)(o0 + (size_t)(row0 + ai * 128 + m * 16) * DFF + col0 + bj * 128);
;         __builtin_amdgcn_sched_barrier(0);
; #pragma unroll
;         for (int m = 0; m < 4; ++m)
; #pragma unroll
;           for (int bj = 0; bj < 2; ++bj) {
;             const f32x4 v0 = acc[ai][bj][m][0], v1 = acc[ai][bj][m][1];
;             const uint4 g = gs[m][bj];
;             f32x4 q0 = {lo2f(g.x) * v0[0], hi2f(g.x) * v0[1], lo2f(g.y) * v0[2], hi2f(g.y) * v0[3]};
;             f32x4 q1 = {lo2f(g.z) * v1[0], hi2f(g.z) * v1[1], lo2f(g.w) * v1[2], hi2f(g.w) * v1[3]};
;             st8(o0 + (size_t)(row0 + ai * 128 + m * 16) * DFF + col0 + bj * 128, q0, q1);
;           }
;         __builtin_amdgcn_sched_barrier(0);
;       }
; DI void conv_phase(const Params& p, int l) {
;     ...
;     float w0[8], w1[8], w2[8], bb[8];
;     load8f(cw + c0, w0); load8f(cw + DFF + c0, w1); load8f(cw + 2 * DFF + c0, w2); load8f(cb + c0, bb);
;     float prev[8], cur[8], nxt[8];
;     unpack8(rows[0], prev); unpack8(rows[1], cur);
; #pragma unroll
;     for (int i = 0; i < RUN; ++i) {
;       unpack8(rows[i + 2], nxt);
;       float o[8];
; #pragma unroll
;       for (int j = 0; j < 8; ++j) { const float g = w0[j] * prev[j] + w1[j] * cur[j] + w2[j] * nxt[j] + bb[j]; o[j] = g * sigmoidf_(g); }
;       uint4 oo; oo.x = pack2(o[0], o[1]); oo.y = pack2(o[2], o[3]); oo.z = pack2(o[4], o[5]); oo.w = pack2(o[6], o[7]);
;       *(uint4*)(GS + (size_t)(t0 + i) * DFF + c0) = oo;
	v_fma_f32 v255, v151, v253, v255
	v_mul_f32_e32 v240, 0xbfb8aa3b, v254
	v_mul_f32_e32 v241, 0xbfb8aa3b, v255
	v_exp_f32_e32 v240, v240
	v_exp_f32_e32 v241, v241
	v_add_f32_e32 v240, 1.0, v240
	v_add_f32_e32 v241, 1.0, v241
	v_rcp_f32_e32 v240, v240
	v_rcp_f32_e32 v241, v241
	v_mul_f32_e32 v254, v254, v240
	v_mul_f32_e32 v255, v255, v241
	v_mul_f32_e32 v254, v254, v18
	v_mul_f32_e32 v255, v255, v19
	v_cvt_pk_bf16_f32 v250, v254, v255
	v_lshlrev_b32_e32 v240, 16, v201
	v_and_b32_e32 v241, 0xffff0000, v201
	v_lshlrev_b32_e32 v242, 16, v205
	v_and_b32_e32 v243, 0xffff0000, v205
	v_lshlrev_b32_e32 v252, 16, v209
	v_and_b32_e32 v253, 0xffff0000, v209
	v_fma_f32 v254, v136, v240, v160
	v_fma_f32 v255, v137, v241, v161
	v_fma_f32 v254, v144, v242, v254
	v_fma_f32 v255, v145, v243, v255
	v_fma_f32 v254, v152, v252, v254
	v_fma_f32 v255, v153, v253, v255
	v_mul_f32_e32 v240, 0xbfb8aa3b, v254
	v_mul_f32_e32 v241, 0xbfb8aa3b, v255
	v_exp_f32_e32 v240, v240
	v_exp_f32_e32 v241, v241
	v_add_f32_e32 v240, 1.0, v240
	v_add_f32_e32 v241, 1.0, v241
	v_rcp_f32_e32 v240, v240
	v_rcp_f32_e32 v241, v241
	v_mul_f32_e32 v254, v254, v240
	v_mul_f32_e32 v255, v255, v241
	v_mul_f32_e32 v254, v254, v20
	v_mul_f32_e32 v255, v255, v21
	v_cvt_pk_bf16_f32 v251, v254, v255
	global_store_dwordx4 v[220:221], v[248:251], off
	v_readlane_b32 s98, v237, 62
	v_readlane_b32 s100, v238, 0
	v_readlane_b32 s101, v238, 1
	s_mul_i32 s98, s98, 0xab
	s_bfe_u32 s98, s98, 0x6000a
	s_mul_i32 s99, s98, 0x8400
	s_add_u32 s100, s100, s99
	s_addc_u32 s101, s101, 0
	s_nop 3
	global_load_dwordx4 v[130:133], v182, s[100:101] offset:512
	global_load_dwordx4 v[134:137], v182, s[100:101] offset:528
	s_add_u32 s100, s100, 0x2c00
	s_addc_u32 s101, s101, 0
	global_load_dwordx4 v[138:141], v182, s[100:101] offset:512
	global_load_dwordx4 v[142:145], v182, s[100:101] offset:528
	s_add_u32 s100, s100, 0x2c00
	s_addc_u32 s101, s101, 0
	global_load_dwordx4 v[146:149], v182, s[100:101] offset:512
	global_load_dwordx4 v[150:153], v182, s[100:101] offset:528
	v_readlane_b32 s100, v238, 2
	v_readlane_b32 s101, v238, 3
	s_mul_i32 s99, s98, 0x2c00
	s_add_u32 s100, s100, s99
	s_addc_u32 s101, s101, 0
	s_nop 3
	global_load_dwordx4 v[154:157], v182, s[100:101] offset:512
	global_load_dwordx4 v[158:161], v182, s[100:101] offset:528
	s_mov_b32 s98, 0x1600
	s_mov_b32 s99, 0
	s_mov_b32 s100, 0x16000000
	s_mov_b32 s101, 0
	v_add_u32_e32 v183, -1, v176
	v_mad_i64_i32 v[222:223], s[0:1], v183, s14, v[180:181]
	v_lshl_add_u64 v[224:225], v[222:223], 0, s[98:99]
	v_lshl_add_u64 v[226:227], v[224:225], 0, s[98:99]
	v_lshl_add_u64 v[196:197], v[224:225], 0, s[100:101]
	global_load_dwordx4 v[184:187], v[222:223], off offset:256
	global_load_dwordx4 v[188:191], v[224:225], off offset:256
	global_load_dwordx4 v[192:195], v[226:227], off offset:256
	v_add_u32_e32 v183, 0xf, v176
	v_mad_i64_i32 v[222:223], s[0:1], v183, s14, v[180:181]
	v_lshl_add_u64 v[224:225], v[222:223], 0, s[98:99]
	v_lshl_add_u64 v[226:227], v[224:225], 0, s[98:99]
	v_lshl_add_u64 v[220:221], v[224:225], 0, s[100:101]
	global_load_dwordx4 v[198:201], v[222:223], off offset:256
	global_load_dwordx4 v[202:205], v[224:225], off offset:256
	global_load_dwordx4 v[206:209], v[226:227], off offset:256
	s_waitcnt vmcnt(3)
	v_and_b32_e32 v183, 0x1fff, v176
	v_cmp_eq_u32_e32 vcc, 0, v183
	v_cndmask_b32_e64 v184, v184, 0, vcc
	v_cndmask_b32_e64 v185, v185, 0, vcc
	v_cndmask_b32_e64 v186, v186, 0, vcc
	v_cndmask_b32_e64 v187, v187, 0, vcc
	v_lshlrev_b32_e32 v240, 16, v184
	v_and_b32_e32 v241, 0xffff0000, v184
	v_lshlrev_b32_e32 v242, 16, v188
	v_and_b32_e32 v243, 0xffff0000, v188
	v_lshlrev_b32_e32 v252, 16, v192
	v_and_b32_e32 v253, 0xffff0000, v192
	v_fma_f32 v254, v130, v240, v154
	v_fma_f32 v255, v131, v241, v155
	v_fma_f32 v254, v138, v242, v254
	v_fma_f32 v255, v139, v243, v255
	v_fma_f32 v254, v146, v252, v254
	v_fma_f32 v255, v147, v253, v255
	v_mul_f32_e32 v240, 0xbfb8aa3b, v254
	v_mul_f32_e32 v241, 0xbfb8aa3b, v255
	v_exp_f32_e32 v240, v240
	v_exp_f32_e32 v241, v241
	v_add_f32_e32 v240, 1.0, v240
	v_add_f32_e32 v241, 1.0, v241
	v_rcp_f32_e32 v240, v240
	v_rcp_f32_e32 v241, v241
	v_mul_f32_e32 v254, v254, v240
	v_mul_f32_e32 v255, v255, v241
	v_mul_f32_e32 v254, v254, v110
	v_mul_f32_e32 v255, v255, v111
	v_cvt_pk_bf16_f32 v244, v254, v255
	v_lshlrev_b32_e32 v240, 16, v185
	v_and_b32_e32 v241, 0xffff0000, v185
	v_lshlrev_b32_e32 v242, 16, v189
	v_and_b32_e32 v243, 0xffff0000, v189
	v_lshlrev_b32_e32 v252, 16, v193
	v_and_b32_e32 v253, 0xffff0000, v193
	v_fma_f32 v254, v132, v240, v156
	v_fma_f32 v255, v133, v241, v157
	v_fma_f32 v254, v140, v242, v254
	v_fma_f32 v255, v141, v243, v255
	v_fma_f32 v254, v148, v252, v254
	v_fma_f32 v255, v149, v253, v255
	v_mul_f32_e32 v240, 0xbfb8aa3b, v254
	v_mul_f32_e32 v241, 0xbfb8aa3b, v255
	v_exp_f32_e32 v240, v240
	v_exp_f32_e32 v241, v241
	v_add_f32_e32 v240, 1.0, v240
	v_add_f32_e32 v241, 1.0, v241
	v_rcp_f32_e32 v240, v240
	v_rcp_f32_e32 v241, v241
	v_mul_f32_e32 v254, v254, v240
	v_mul_f32_e32 v255, v255, v241
	v_mul_f32_e32 v254, v254, v112
	v_mul_f32_e32 v255, v255, v113
	v_cvt_pk_bf16_f32 v245, v254, v255
	v_lshlrev_b32_e32 v240, 16, v186
	v_and_b32_e32 v241, 0xffff0000, v186
	v_lshlrev_b32_e32 v242, 16, v190
	v_and_b32_e32 v243, 0xffff0000, v190
	v_lshlrev_b32_e32 v252, 16, v194
	v_and_b32_e32 v253, 0xffff0000, v194
	v_fma_f32 v254, v134, v240, v158
	v_fma_f32 v255, v135, v241, v159
	v_fma_f32 v254, v142, v242, v254
	v_fma_f32 v255, v143, v243, v255
	v_fma_f32 v254, v150, v252, v254
	v_fma_f32 v255, v151, v253, v255
	v_mul_f32_e32 v240, 0xbfb8aa3b, v254
	v_mul_f32_e32 v241, 0xbfb8aa3b, v255
	v_exp_f32_e32 v240, v240
; DI unsigned pack2(float a, float b) { f32x2_t v = {a, b}; bf16x2_t r = __builtin_convertvector(v, bf16x2_t); return __builtin_bit_cast(unsigned, r); }
; DI float lo2f(unsigned u) { return __uint_as_float(u << 16); }
; DI float hi2f(unsigned u) { return __uint_as_float(u & 0xffff0000u); }
; DI float sigmoidf_(float x) { return __builtin_amdgcn_rcpf(1.f + __builtin_amdgcn_exp2f(-1.4426950408889634f * x)); }
;   DI void operator()(const f32x4 (&acc)[2][2][4][2], const pg8::Unit& u, int wr, int wc, int fr, int fq) const {
;     ...
;     } else {
; #pragma unroll
;       for (int ai = 0; ai < 2; ++ai) {
;         uint4 gs[4][2];
; #pragma unroll
;         for (int m = 0; m < 4; ++m)
; #pragma unroll
;           for (int bj = 0; bj < 2; ++bj)
;             gs[m][bj] = *(const uint4*)(o0 + (size_t)(row0 + ai * 128 + m * 16) * DFF + col0 + bj * 128);
;         __builtin_amdgcn_sched_barrier(0);
; #pragma unroll
;         for (int m = 0; m < 4; ++m)
; #pragma unroll
;           for (int bj = 0; bj < 2; ++bj) {
;             const f32x4 v0 = acc[ai][bj][m][0], v1 = acc[ai][bj][m][1];
;             const uint4 g = gs[m][bj];
;             f32x4 q0 = {lo2f(g.x) * v0[0], hi2f(g.x) * v0[1], lo2f(g.y) * v0[2], hi2f(g.y) * v0[3]};
;             f32x4 q1 = {lo2f(g.z) * v1[0], hi2f(g.z) * v1[1], lo2f(g.w) * v1[2], hi2f(g.w) * v1[3]};
;             st8(o0 + (size_t)(row0 + ai * 128 + m * 16) * DFF + col0 + bj * 128, q0, q1);
;           }
;         __builtin_amdgcn_sched_barrier(0);
;       }
; DI void conv_phase(const Params& p, int l) {
;     ...
;     for (int i = 0; i < RUN; ++i) {
;       unpack8(rows[i + 2], nxt);
;       float o[8];
; #pragma unroll
;       for (int j = 0; j < 8; ++j) { const float g = w0[j] * prev[j] + w1[j] * cur[j] + w2[j] * nxt[j] + bb[j]; o[j] = g * sigmoidf_(g); }
;       uint4 oo; oo.x = pack2(o[0], o[1]); oo.y = pack2(o[2], o[3]); oo.z = pack2(o[4], o[5]); oo.w = pack2(o[6], o[7]);
;       *(uint4*)(GS + (size_t)(t0 + i) * DFF + c0) = oo;
	v_exp_f32_e32 v241, v241
	v_add_f32_e32 v240, 1.0, v240
	v_add_f32_e32 v241, 1.0, v241
	v_rcp_f32_e32 v240, v240
	v_rcp_f32_e32 v241, v241
	v_mul_f32_e32 v254, v254, v240
	v_mul_f32_e32 v255, v255, v241
	v_mul_f32_e32 v254, v254, v106
	v_mul_f32_e32 v255, v255, v107
	v_cvt_pk_bf16_f32 v246, v254, v255
	v_lshlrev_b32_e32 v240, 16, v187
	v_and_b32_e32 v241, 0xffff0000, v187
	v_lshlrev_b32_e32 v242, 16, v191
	v_and_b32_e32 v243, 0xffff0000, v191
	v_lshlrev_b32_e32 v252, 16, v195
	v_and_b32_e32 v253, 0xffff0000, v195
	v_fma_f32 v254, v136, v240, v160
	v_fma_f32 v255, v137, v241, v161
	v_fma_f32 v254, v144, v242, v254
	v_fma_f32 v255, v145, v243, v255
	v_fma_f32 v254, v152, v252, v254
	v_fma_f32 v255, v153, v253, v255
	v_mul_f32_e32 v240, 0xbfb8aa3b, v254
	v_mul_f32_e32 v241, 0xbfb8aa3b, v255
	v_exp_f32_e32 v240, v240
	v_exp_f32_e32 v241, v241
	v_add_f32_e32 v240, 1.0, v240
	v_add_f32_e32 v241, 1.0, v241
	v_rcp_f32_e32 v240, v240
	v_rcp_f32_e32 v241, v241
	v_mul_f32_e32 v254, v254, v240
	v_mul_f32_e32 v255, v255, v241
	v_mul_f32_e32 v254, v254, v108
	v_mul_f32_e32 v255, v255, v109
	v_cvt_pk_bf16_f32 v247, v254, v255
	global_store_dwordx4 v[196:197], v[244:247], off offset:256
	v_add_u32_e32 v183, 0x1f, v176
	v_mad_i64_i32 v[222:223], s[0:1], v183, s14, v[180:181]
	v_lshl_add_u64 v[224:225], v[222:223], 0, s[98:99]
	v_lshl_add_u64 v[226:227], v[224:225], 0, s[98:99]
	v_lshl_add_u64 v[196:197], v[224:225], 0, s[100:101]
	global_load_dwordx4 v[184:187], v[222:223], off offset:256
	global_load_dwordx4 v[188:191], v[224:225], off offset:256
	global_load_dwordx4 v[192:195], v[226:227], off offset:256
	s_waitcnt vmcnt(4)
	v_lshlrev_b32_e32 v240, 16, v198
	v_and_b32_e32 v241, 0xffff0000, v198
	v_lshlrev_b32_e32 v242, 16, v202
	v_and_b32_e32 v243, 0xffff0000, v202
	v_lshlrev_b32_e32 v252, 16, v206
	v_and_b32_e32 v253, 0xffff0000, v206
	v_fma_f32 v254, v130, v240, v154
	v_fma_f32 v255, v131, v241, v155
	v_fma_f32 v254, v138, v242, v254
	v_fma_f32 v255, v139, v243, v255
	v_fma_f32 v254, v146, v252, v254
	v_fma_f32 v255, v147, v253, v255
	v_mul_f32_e32 v240, 0xbfb8aa3b, v254
	v_mul_f32_e32 v241, 0xbfb8aa3b, v255
	v_exp_f32_e32 v240, v240
	v_exp_f32_e32 v241, v241
	v_add_f32_e32 v240, 1.0, v240
	v_add_f32_e32 v241, 1.0, v241
	v_rcp_f32_e32 v240, v240
	v_rcp_f32_e32 v241, v241
	v_mul_f32_e32 v254, v254, v240
	v_mul_f32_e32 v255, v255, v241
	v_mul_f32_e32 v254, v254, v94
	v_mul_f32_e32 v255, v255, v95
	v_cvt_pk_bf16_f32 v248, v254, v255
	v_lshlrev_b32_e32 v240, 16, v199
	v_and_b32_e32 v241, 0xffff0000, v199
	v_lshlrev_b32_e32 v242, 16, v203
	v_and_b32_e32 v243, 0xffff0000, v203
	v_lshlrev_b32_e32 v252, 16, v207
	v_and_b32_e32 v253, 0xffff0000, v207
	v_fma_f32 v254, v132, v240, v156
	v_fma_f32 v255, v133, v241, v157
	v_fma_f32 v254, v140, v242, v254
	v_fma_f32 v255, v141, v243, v255
	v_fma_f32 v254, v148, v252, v254
	v_fma_f32 v255, v149, v253, v255
	v_mul_f32_e32 v240, 0xbfb8aa3b, v254
	v_mul_f32_e32 v241, 0xbfb8aa3b, v255
	v_exp_f32_e32 v240, v240
	v_exp_f32_e32 v241, v241
	v_add_f32_e32 v240, 1.0, v240
	v_add_f32_e32 v241, 1.0, v241
	v_rcp_f32_e32 v240, v240
	v_rcp_f32_e32 v241, v241
	v_mul_f32_e32 v254, v254, v240
	v_mul_f32_e32 v255, v255, v241
	v_mul_f32_e32 v254, v254, v96
	v_mul_f32_e32 v255, v255, v97
	v_cvt_pk_bf16_f32 v249, v254, v255
	v_lshlrev_b32_e32 v240, 16, v200
	v_and_b32_e32 v241, 0xffff0000, v200
	v_lshlrev_b32_e32 v242, 16, v204
	v_and_b32_e32 v243, 0xffff0000, v204
	v_lshlrev_b32_e32 v252, 16, v208
	v_and_b32_e32 v253, 0xffff0000, v208
	v_fma_f32 v254, v134, v240, v158
	v_fma_f32 v255, v135, v241, v159
	v_fma_f32 v254, v142, v242, v254
	v_fma_f32 v255, v143, v243, v255
	v_fma_f32 v254, v150, v252, v254
	v_fma_f32 v255, v151, v253, v255
	v_mul_f32_e32 v240, 0xbfb8aa3b, v254
	v_mul_f32_e32 v241, 0xbfb8aa3b, v255
	v_exp_f32_e32 v240, v240
	v_exp_f32_e32 v241, v241
	v_add_f32_e32 v240, 1.0, v240
	v_add_f32_e32 v241, 1.0, v241
	v_rcp_f32_e32 v240, v240
	v_rcp_f32_e32 v241, v241
	v_mul_f32_e32 v254, v254, v240
	v_mul_f32_e32 v255, v255, v241
	v_mul_f32_e32 v254, v254, v90
	v_mul_f32_e32 v255, v255, v91
	v_cvt_pk_bf16_f32 v250, v254, v255
	v_lshlrev_b32_e32 v240, 16, v201
	v_and_b32_e32 v241, 0xffff0000, v201
	v_lshlrev_b32_e32 v242, 16, v205
	v_and_b32_e32 v243, 0xffff0000, v205
	v_lshlrev_b32_e32 v252, 16, v209
	v_and_b32_e32 v253, 0xffff0000, v209
	v_fma_f32 v254, v136, v240, v160
	v_fma_f32 v255, v137, v241, v161
	v_fma_f32 v254, v144, v242, v254
	v_fma_f32 v255, v145, v243, v255
	v_fma_f32 v254, v152, v252, v254
	v_fma_f32 v255, v153, v253, v255
	v_mul_f32_e32 v240, 0xbfb8aa3b, v254
	v_mul_f32_e32 v241, 0xbfb8aa3b, v255
	v_exp_f32_e32 v240, v240
	v_exp_f32_e32 v241, v241
	v_add_f32_e32 v240, 1.0, v240
	v_add_f32_e32 v241, 1.0, v241
	v_rcp_f32_e32 v240, v240
	v_rcp_f32_e32 v241, v241
	v_mul_f32_e32 v254, v254, v240
	v_mul_f32_e32 v255, v255, v241
	v_mul_f32_e32 v254, v254, v92
	v_mul_f32_e32 v255, v255, v93
	v_cvt_pk_bf16_f32 v251, v254, v255
	global_store_dwordx4 v[220:221], v[248:251], off offset:256
	v_add_u32_e32 v183, 0x2f, v176
	v_mad_i64_i32 v[222:223], s[0:1], v183, s14, v[180:181]
	v_lshl_add_u64 v[224:225], v[222:223], 0, s[98:99]
	v_lshl_add_u64 v[226:227], v[224:225], 0, s[98:99]
	v_lshl_add_u64 v[220:221], v[224:225], 0, s[100:101]
	global_load_dwordx4 v[198:201], v[222:223], off offset:256
	global_load_dwordx4 v[202:205], v[224:225], off offset:256
	global_load_dwordx4 v[206:209], v[226:227], off offset:256
	s_waitcnt vmcnt(4)
; DI unsigned pack2(float a, float b) { f32x2_t v = {a, b}; bf16x2_t r = __builtin_convertvector(v, bf16x2_t); return __builtin_bit_cast(unsigned, r); }
; DI float lo2f(unsigned u) { return __uint_as_float(u << 16); }
; DI float hi2f(unsigned u) { return __uint_as_float(u & 0xffff0000u); }
; DI float sigmoidf_(float x) { return __builtin_amdgcn_rcpf(1.f + __builtin_amdgcn_exp2f(-1.4426950408889634f * x)); }
;   DI void operator()(const f32x4 (&acc)[2][2][4][2], const pg8::Unit& u, int wr, int wc, int fr, int fq) const {
;     ...
;     } else {
; #pragma unroll
;       for (int ai = 0; ai < 2; ++ai) {
;         uint4 gs[4][2];
; #pragma unroll
;         for (int m = 0; m < 4; ++m)
; #pragma unroll
;           for (int bj = 0; bj < 2; ++bj)
;             gs[m][bj] = *(const uint4*)(o0 + (size_t)(row0 + ai * 128 + m * 16) * DFF + col0 + bj * 128);
;         __builtin_amdgcn_sched_barrier(0);
; #pragma unroll
;         for (int m = 0; m < 4; ++m)
; #pragma unroll
;           for (int bj = 0; bj < 2; ++bj) {
;             const f32x4 v0 = acc[ai][bj][m][0], v1 = acc[ai][bj][m][1];
;             const uint4 g = gs[m][bj];
;             f32x4 q0 = {lo2f(g.x) * v0[0], hi2f(g.x) * v0[1], lo2f(g.y) * v0[2], hi2f(g.y) * v0[3]};
;             f32x4 q1 = {lo2f(g.z) * v1[0], hi2f(g.z) * v1[1], lo2f(g.w) * v1[2], hi2f(g.w) * v1[3]};
;             st8(o0 + (size_t)(row0 + ai * 128 + m * 16) * DFF + col0 + bj * 128, q0, q1);
;           }
;         __builtin_amdgcn_sched_barrier(0);
;       }
; DI void conv_phase(const Params& p, int l) {
;     ...
;     for (int i = 0; i < RUN; ++i) {
;       unpack8(rows[i + 2], nxt);
;       float o[8];
; #pragma unroll
;       for (int j = 0; j < 8; ++j) { const float g = w0[j] * prev[j] + w1[j] * cur[j] + w2[j] * nxt[j] + bb[j]; o[j] = g * sigmoidf_(g); }
;       uint4 oo; oo.x = pack2(o[0], o[1]); oo.y = pack2(o[2], o[3]); oo.z = pack2(o[4], o[5]); oo.w = pack2(o[6], o[7]);
;       *(uint4*)(GS + (size_t)(t0 + i) * DFF + c0) = oo;
	v_lshlrev_b32_e32 v240, 16, v184
	v_and_b32_e32 v241, 0xffff0000, v184
	v_lshlrev_b32_e32 v242, 16, v188
	v_and_b32_e32 v243, 0xffff0000, v188
	v_lshlrev_b32_e32 v252, 16, v192
	v_and_b32_e32 v253, 0xffff0000, v192
	v_fma_f32 v254, v130, v240, v154
	v_fma_f32 v255, v131, v241, v155
	v_fma_f32 v254, v138, v242, v254
	v_fma_f32 v255, v139, v243, v255
	v_fma_f32 v254, v146, v252, v254
	v_fma_f32 v255, v147, v253, v255
	v_mul_f32_e32 v240, 0xbfb8aa3b, v254
	v_mul_f32_e32 v241, 0xbfb8aa3b, v255
	v_exp_f32_e32 v240, v240
	v_exp_f32_e32 v241, v241
	v_add_f32_e32 v240, 1.0, v240
	v_add_f32_e32 v241, 1.0, v241
	v_rcp_f32_e32 v240, v240
	v_rcp_f32_e32 v241, v241
	v_mul_f32_e32 v254, v254, v240
	v_mul_f32_e32 v255, v255, v241
	v_mul_f32_e32 v254, v254, v78
	v_mul_f32_e32 v255, v255, v79
	v_cvt_pk_bf16_f32 v244, v254, v255
	v_lshlrev_b32_e32 v240, 16, v185
	v_and_b32_e32 v241, 0xffff0000, v185
	v_lshlrev_b32_e32 v242, 16, v189
	v_and_b32_e32 v243, 0xffff0000, v189
	v_lshlrev_b32_e32 v252, 16, v193
	v_and_b32_e32 v253, 0xffff0000, v193
	v_fma_f32 v254, v132, v240, v156
	v_fma_f32 v255, v133, v241, v157
	v_fma_f32 v254, v140, v242, v254
	v_fma_f32 v255, v141, v243, v255
	v_fma_f32 v254, v148, v252, v254
	v_fma_f32 v255, v149, v253, v255
	v_mul_f32_e32 v240, 0xbfb8aa3b, v254
	v_mul_f32_e32 v241, 0xbfb8aa3b, v255
	v_exp_f32_e32 v240, v240
	v_exp_f32_e32 v241, v241
	v_add_f32_e32 v240, 1.0, v240
	v_add_f32_e32 v241, 1.0, v241
	v_rcp_f32_e32 v240, v240
	v_rcp_f32_e32 v241, v241
	v_mul_f32_e32 v254, v254, v240
	v_mul_f32_e32 v255, v255, v241
	v_mul_f32_e32 v254, v254, v80
	v_mul_f32_e32 v255, v255, v81
	v_cvt_pk_bf16_f32 v245, v254, v255
	v_lshlrev_b32_e32 v240, 16, v186
	v_and_b32_e32 v241, 0xffff0000, v186
	v_lshlrev_b32_e32 v242, 16, v190
	v_and_b32_e32 v243, 0xffff0000, v190
	v_lshlrev_b32_e32 v252, 16, v194
	v_and_b32_e32 v253, 0xffff0000, v194
	v_fma_f32 v254, v134, v240, v158
	v_fma_f32 v255, v135, v241, v159
	v_fma_f32 v254, v142, v242, v254
	v_fma_f32 v255, v143, v243, v255
	v_fma_f32 v254, v150, v252, v254
	v_fma_f32 v255, v151, v253, v255
	v_mul_f32_e32 v240, 0xbfb8aa3b, v254
	v_mul_f32_e32 v241, 0xbfb8aa3b, v255
	v_exp_f32_e32 v240, v240
	v_exp_f32_e32 v241, v241
	v_add_f32_e32 v240, 1.0, v240
	v_add_f32_e32 v241, 1.0, v241
	v_rcp_f32_e32 v240, v240
	v_rcp_f32_e32 v241, v241
	v_mul_f32_e32 v254, v254, v240
	v_mul_f32_e32 v255, v255, v241
	v_mul_f32_e32 v254, v254, v74
	v_mul_f32_e32 v255, v255, v75
	v_cvt_pk_bf16_f32 v246, v254, v255
	v_lshlrev_b32_e32 v240, 16, v187
	v_and_b32_e32 v241, 0xffff0000, v187
	v_lshlrev_b32_e32 v242, 16, v191
	v_and_b32_e32 v243, 0xffff0000, v191
	v_lshlrev_b32_e32 v252, 16, v195
	v_and_b32_e32 v253, 0xffff0000, v195
	v_fma_f32 v254, v136, v240, v160
	v_fma_f32 v255, v137, v241, v161
	v_fma_f32 v254, v144, v242, v254
	v_fma_f32 v255, v145, v243, v255
	v_fma_f32 v254, v152, v252, v254
	v_fma_f32 v255, v153, v253, v255
	v_mul_f32_e32 v240, 0xbfb8aa3b, v254
	v_mul_f32_e32 v241, 0xbfb8aa3b, v255
	v_exp_f32_e32 v240, v240
	v_exp_f32_e32 v241, v241
	v_add_f32_e32 v240, 1.0, v240
	v_add_f32_e32 v241, 1.0, v241
	v_rcp_f32_e32 v240, v240
	v_rcp_f32_e32 v241, v241
	v_mul_f32_e32 v254, v254, v240
	v_mul_f32_e32 v255, v255, v241
	v_mul_f32_e32 v254, v254, v76
	v_mul_f32_e32 v255, v255, v77
	v_cvt_pk_bf16_f32 v247, v254, v255
	global_store_dwordx4 v[196:197], v[244:247], off offset:256
	v_add_u32_e32 v183, 0x7f, v176
	v_mad_i64_i32 v[222:223], s[0:1], v183, s14, v[180:181]
	v_lshl_add_u64 v[224:225], v[222:223], 0, s[98:99]
	v_lshl_add_u64 v[226:227], v[224:225], 0, s[98:99]
	v_lshl_add_u64 v[196:197], v[224:225], 0, s[100:101]
	global_load_dwordx4 v[184:187], v[222:223], off offset:256
	global_load_dwordx4 v[188:191], v[224:225], off offset:256
	global_load_dwordx4 v[192:195], v[226:227], off offset:256
	s_waitcnt vmcnt(4)
	v_lshlrev_b32_e32 v240, 16, v198
	v_and_b32_e32 v241, 0xffff0000, v198
	v_lshlrev_b32_e32 v242, 16, v202
	v_and_b32_e32 v243, 0xffff0000, v202
	v_lshlrev_b32_e32 v252, 16, v206
	v_and_b32_e32 v253, 0xffff0000, v206
	v_fma_f32 v254, v130, v240, v154
	v_fma_f32 v255, v131, v241, v155
	v_fma_f32 v254, v138, v242, v254
	v_fma_f32 v255, v139, v243, v255
	v_fma_f32 v254, v146, v252, v254
	v_fma_f32 v255, v147, v253, v255
	v_mul_f32_e32 v240, 0xbfb8aa3b, v254
	v_mul_f32_e32 v241, 0xbfb8aa3b, v255
	v_exp_f32_e32 v240, v240
	v_exp_f32_e32 v241, v241
	v_add_f32_e32 v240, 1.0, v240
	v_add_f32_e32 v241, 1.0, v241
	v_rcp_f32_e32 v240, v240
	v_rcp_f32_e32 v241, v241
	v_mul_f32_e32 v254, v254, v240
	v_mul_f32_e32 v255, v255, v241
	v_mul_f32_e32 v254, v254, v70
	v_mul_f32_e32 v255, v255, v71
	v_cvt_pk_bf16_f32 v248, v254, v255
	v_lshlrev_b32_e32 v240, 16, v199
	v_and_b32_e32 v241, 0xffff0000, v199
	v_lshlrev_b32_e32 v242, 16, v203
	v_and_b32_e32 v243, 0xffff0000, v203
	v_lshlrev_b32_e32 v252, 16, v207
	v_and_b32_e32 v253, 0xffff0000, v207
	v_fma_f32 v254, v132, v240, v156
	v_fma_f32 v255, v133, v241, v157
	v_fma_f32 v254, v140, v242, v254
	v_fma_f32 v255, v141, v243, v255
	v_fma_f32 v254, v148, v252, v254
	v_fma_f32 v255, v149, v253, v255
	v_mul_f32_e32 v240, 0xbfb8aa3b, v254
	v_mul_f32_e32 v241, 0xbfb8aa3b, v255
	v_exp_f32_e32 v240, v240
	v_exp_f32_e32 v241, v241
	v_add_f32_e32 v240, 1.0, v240
	v_add_f32_e32 v241, 1.0, v241
	v_rcp_f32_e32 v240, v240
	v_rcp_f32_e32 v241, v241
	v_mul_f32_e32 v254, v254, v240
	v_mul_f32_e32 v255, v255, v241
	v_mul_f32_e32 v254, v254, v72
	v_mul_f32_e32 v255, v255, v73
	v_cvt_pk_bf16_f32 v249, v254, v255
	v_lshlrev_b32_e32 v240, 16, v200
	v_and_b32_e32 v241, 0xffff0000, v200
	v_lshlrev_b32_e32 v242, 16, v204
	v_and_b32_e32 v243, 0xffff0000, v204
	v_lshlrev_b32_e32 v252, 16, v208
; DI unsigned pack2(float a, float b) { f32x2_t v = {a, b}; bf16x2_t r = __builtin_convertvector(v, bf16x2_t); return __builtin_bit_cast(unsigned, r); }
; DI float lo2f(unsigned u) { return __uint_as_float(u << 16); }
; DI float hi2f(unsigned u) { return __uint_as_float(u & 0xffff0000u); }
; DI float sigmoidf_(float x) { return __builtin_amdgcn_rcpf(1.f + __builtin_amdgcn_exp2f(-1.4426950408889634f * x)); }
;   DI void operator()(const f32x4 (&acc)[2][2][4][2], const pg8::Unit& u, int wr, int wc, int fr, int fq) const {
;     ...
;     } else {
; #pragma unroll
;       for (int ai = 0; ai < 2; ++ai) {
;         uint4 gs[4][2];
; #pragma unroll
;         for (int m = 0; m < 4; ++m)
; #pragma unroll
;           for (int bj = 0; bj < 2; ++bj)
;             gs[m][bj] = *(const uint4*)(o0 + (size_t)(row0 + ai * 128 + m * 16) * DFF + col0 + bj * 128);
;         __builtin_amdgcn_sched_barrier(0);
; #pragma unroll
;         for (int m = 0; m < 4; ++m)
; #pragma unroll
;           for (int bj = 0; bj < 2; ++bj) {
;             const f32x4 v0 = acc[ai][bj][m][0], v1 = acc[ai][bj][m][1];
;             const uint4 g = gs[m][bj];
;             f32x4 q0 = {lo2f(g.x) * v0[0], hi2f(g.x) * v0[1], lo2f(g.y) * v0[2], hi2f(g.y) * v0[3]};
;             f32x4 q1 = {lo2f(g.z) * v1[0], hi2f(g.z) * v1[1], lo2f(g.w) * v1[2], hi2f(g.w) * v1[3]};
;             st8(o0 + (size_t)(row0 + ai * 128 + m * 16) * DFF + col0 + bj * 128, q0, q1);
;           }
;         __builtin_amdgcn_sched_barrier(0);
;       }
; DI void conv_phase(const Params& p, int l) {
;     ...
;     for (int i = 0; i < RUN; ++i) {
;       unpack8(rows[i + 2], nxt);
;       float o[8];
; #pragma unroll
;       for (int j = 0; j < 8; ++j) { const float g = w0[j] * prev[j] + w1[j] * cur[j] + w2[j] * nxt[j] + bb[j]; o[j] = g * sigmoidf_(g); }
;       uint4 oo; oo.x = pack2(o[0], o[1]); oo.y = pack2(o[2], o[3]); oo.z = pack2(o[4], o[5]); oo.w = pack2(o[6], o[7]);
;       *(uint4*)(GS + (size_t)(t0 + i) * DFF + c0) = oo;
	v_and_b32_e32 v253, 0xffff0000, v208
	v_fma_f32 v254, v134, v240, v158
	v_fma_f32 v255, v135, v241, v159
	v_fma_f32 v254, v142, v242, v254
	v_fma_f32 v255, v143, v243, v255
	v_fma_f32 v254, v150, v252, v254
	v_fma_f32 v255, v151, v253, v255
	v_mul_f32_e32 v240, 0xbfb8aa3b, v254
	v_mul_f32_e32 v241, 0xbfb8aa3b, v255
	v_exp_f32_e32 v240, v240
	v_exp_f32_e32 v241, v241
	v_add_f32_e32 v240, 1.0, v240
	v_add_f32_e32 v241, 1.0, v241
	v_rcp_f32_e32 v240, v240
	v_rcp_f32_e32 v241, v241
	v_mul_f32_e32 v254, v254, v240
	v_mul_f32_e32 v255, v255, v241
	v_mul_f32_e32 v254, v254, v66
	v_mul_f32_e32 v255, v255, v67
	v_cvt_pk_bf16_f32 v250, v254, v255
	v_lshlrev_b32_e32 v240, 16, v201
	v_and_b32_e32 v241, 0xffff0000, v201
	v_lshlrev_b32_e32 v242, 16, v205
	v_and_b32_e32 v243, 0xffff0000, v205
	v_lshlrev_b32_e32 v252, 16, v209
	v_and_b32_e32 v253, 0xffff0000, v209
	v_fma_f32 v254, v136, v240, v160
	v_fma_f32 v255, v137, v241, v161
	v_fma_f32 v254, v144, v242, v254
	v_fma_f32 v255, v145, v243, v255
	v_fma_f32 v254, v152, v252, v254
	v_fma_f32 v255, v153, v253, v255
	v_mul_f32_e32 v240, 0xbfb8aa3b, v254
	v_mul_f32_e32 v241, 0xbfb8aa3b, v255
	v_exp_f32_e32 v240, v240
	v_exp_f32_e32 v241, v241
	v_add_f32_e32 v240, 1.0, v240
	v_add_f32_e32 v241, 1.0, v241
	v_rcp_f32_e32 v240, v240
	v_rcp_f32_e32 v241, v241
	v_mul_f32_e32 v254, v254, v240
	v_mul_f32_e32 v255, v255, v241
	v_mul_f32_e32 v254, v254, v68
	v_mul_f32_e32 v255, v255, v69
	v_cvt_pk_bf16_f32 v251, v254, v255
	global_store_dwordx4 v[220:221], v[248:251], off offset:256
	v_add_u32_e32 v183, 0x8f, v176
	v_mad_i64_i32 v[222:223], s[0:1], v183, s14, v[180:181]
	v_lshl_add_u64 v[224:225], v[222:223], 0, s[98:99]
	v_lshl_add_u64 v[226:227], v[224:225], 0, s[98:99]
	v_lshl_add_u64 v[220:221], v[224:225], 0, s[100:101]
	global_load_dwordx4 v[198:201], v[222:223], off offset:256
	global_load_dwordx4 v[202:205], v[224:225], off offset:256
	global_load_dwordx4 v[206:209], v[226:227], off offset:256
	s_waitcnt vmcnt(4)
	v_lshlrev_b32_e32 v240, 16, v184
	v_and_b32_e32 v241, 0xffff0000, v184
	v_lshlrev_b32_e32 v242, 16, v188
	v_and_b32_e32 v243, 0xffff0000, v188
	v_lshlrev_b32_e32 v252, 16, v192
	v_and_b32_e32 v253, 0xffff0000, v192
	v_fma_f32 v254, v130, v240, v154
	v_fma_f32 v255, v131, v241, v155
	v_fma_f32 v254, v138, v242, v254
	v_fma_f32 v255, v139, v243, v255
	v_fma_f32 v254, v146, v252, v254
	v_fma_f32 v255, v147, v253, v255
	v_mul_f32_e32 v240, 0xbfb8aa3b, v254
	v_mul_f32_e32 v241, 0xbfb8aa3b, v255
	v_exp_f32_e32 v240, v240
	v_exp_f32_e32 v241, v241
	v_add_f32_e32 v240, 1.0, v240
	v_add_f32_e32 v241, 1.0, v241
	v_rcp_f32_e32 v240, v240
	v_rcp_f32_e32 v241, v241
	v_mul_f32_e32 v254, v254, v240
	v_mul_f32_e32 v255, v255, v241
	v_mul_f32_e32 v254, v254, v46
	v_mul_f32_e32 v255, v255, v47
	v_cvt_pk_bf16_f32 v244, v254, v255
	v_lshlrev_b32_e32 v240, 16, v185
	v_and_b32_e32 v241, 0xffff0000, v185
	v_lshlrev_b32_e32 v242, 16, v189
	v_and_b32_e32 v243, 0xffff0000, v189
	v_lshlrev_b32_e32 v252, 16, v193
	v_and_b32_e32 v253, 0xffff0000, v193
	v_fma_f32 v254, v132, v240, v156
	v_fma_f32 v255, v133, v241, v157
	v_fma_f32 v254, v140, v242, v254
	v_fma_f32 v255, v141, v243, v255
	v_fma_f32 v254, v148, v252, v254
	v_fma_f32 v255, v149, v253, v255
	v_mul_f32_e32 v240, 0xbfb8aa3b, v254
	v_mul_f32_e32 v241, 0xbfb8aa3b, v255
	v_exp_f32_e32 v240, v240
	v_exp_f32_e32 v241, v241
	v_add_f32_e32 v240, 1.0, v240
	v_add_f32_e32 v241, 1.0, v241
	v_rcp_f32_e32 v240, v240
	v_rcp_f32_e32 v241, v241
	v_mul_f32_e32 v254, v254, v240
	v_mul_f32_e32 v255, v255, v241
	v_mul_f32_e32 v254, v254, v48
	v_mul_f32_e32 v255, v255, v49
	v_cvt_pk_bf16_f32 v245, v254, v255
	v_lshlrev_b32_e32 v240, 16, v186
	v_and_b32_e32 v241, 0xffff0000, v186
	v_lshlrev_b32_e32 v242, 16, v190
	v_and_b32_e32 v243, 0xffff0000, v190
	v_lshlrev_b32_e32 v252, 16, v194
	v_and_b32_e32 v253, 0xffff0000, v194
	v_fma_f32 v254, v134, v240, v158
	v_fma_f32 v255, v135, v241, v159
	v_fma_f32 v254, v142, v242, v254
	v_fma_f32 v255, v143, v243, v255
	v_fma_f32 v254, v150, v252, v254
	v_fma_f32 v255, v151, v253, v255
	v_mul_f32_e32 v240, 0xbfb8aa3b, v254
	v_mul_f32_e32 v241, 0xbfb8aa3b, v255
	v_exp_f32_e32 v240, v240
	v_exp_f32_e32 v241, v241
	v_add_f32_e32 v240, 1.0, v240
	v_add_f32_e32 v241, 1.0, v241
	v_rcp_f32_e32 v240, v240
	v_rcp_f32_e32 v241, v241
	v_mul_f32_e32 v254, v254, v240
	v_mul_f32_e32 v255, v255, v241
	v_mul_f32_e32 v254, v254, v42
	v_mul_f32_e32 v255, v255, v43
	v_cvt_pk_bf16_f32 v246, v254, v255
	v_lshlrev_b32_e32 v240, 16, v187
	v_and_b32_e32 v241, 0xffff0000, v187
	v_lshlrev_b32_e32 v242, 16, v191
	v_and_b32_e32 v243, 0xffff0000, v191
	v_lshlrev_b32_e32 v252, 16, v195
	v_and_b32_e32 v253, 0xffff0000, v195
	v_fma_f32 v254, v136, v240, v160
	v_fma_f32 v255, v137, v241, v161
	v_fma_f32 v254, v144, v242, v254
	v_fma_f32 v255, v145, v243, v255
	v_fma_f32 v254, v152, v252, v254
	v_fma_f32 v255, v153, v253, v255
	v_mul_f32_e32 v240, 0xbfb8aa3b, v254
	v_mul_f32_e32 v241, 0xbfb8aa3b, v255
	v_exp_f32_e32 v240, v240
	v_exp_f32_e32 v241, v241
	v_add_f32_e32 v240, 1.0, v240
	v_add_f32_e32 v241, 1.0, v241
	v_rcp_f32_e32 v240, v240
	v_rcp_f32_e32 v241, v241
	v_mul_f32_e32 v254, v254, v240
	v_mul_f32_e32 v255, v255, v241
	v_mul_f32_e32 v254, v254, v44
	v_mul_f32_e32 v255, v255, v45
	v_cvt_pk_bf16_f32 v247, v254, v255
	global_store_dwordx4 v[196:197], v[244:247], off offset:256
	v_add_u32_e32 v183, 0x9f, v176
	v_mad_i64_i32 v[222:223], s[0:1], v183, s14, v[180:181]
	v_lshl_add_u64 v[224:225], v[222:223], 0, s[98:99]
	v_lshl_add_u64 v[226:227], v[224:225], 0, s[98:99]
	v_lshl_add_u64 v[196:197], v[224:225], 0, s[100:101]
	global_load_dwordx4 v[184:187], v[222:223], off offset:256
	global_load_dwordx4 v[188:191], v[224:225], off offset:256
	global_load_dwordx4 v[192:195], v[226:227], off offset:256
	s_waitcnt vmcnt(4)
; DI unsigned pack2(float a, float b) { f32x2_t v = {a, b}; bf16x2_t r = __builtin_convertvector(v, bf16x2_t); return __builtin_bit_cast(unsigned, r); }
; DI float lo2f(unsigned u) { return __uint_as_float(u << 16); }
; DI float hi2f(unsigned u) { return __uint_as_float(u & 0xffff0000u); }
; DI float sigmoidf_(float x) { return __builtin_amdgcn_rcpf(1.f + __builtin_amdgcn_exp2f(-1.4426950408889634f * x)); }
;   DI void operator()(const f32x4 (&acc)[2][2][4][2], const pg8::Unit& u, int wr, int wc, int fr, int fq) const {
;     ...
;     } else {
; #pragma unroll
;       for (int ai = 0; ai < 2; ++ai) {
;         uint4 gs[4][2];
; #pragma unroll
;         for (int m = 0; m < 4; ++m)
; #pragma unroll
;           for (int bj = 0; bj < 2; ++bj)
;             gs[m][bj] = *(const uint4*)(o0 + (size_t)(row0 + ai * 128 + m * 16) * DFF + col0 + bj * 128);
;         __builtin_amdgcn_sched_barrier(0);
; #pragma unroll
;         for (int m = 0; m < 4; ++m)
; #pragma unroll
;           for (int bj = 0; bj < 2; ++bj) {
;             const f32x4 v0 = acc[ai][bj][m][0], v1 = acc[ai][bj][m][1];
;             const uint4 g = gs[m][bj];
;             f32x4 q0 = {lo2f(g.x) * v0[0], hi2f(g.x) * v0[1], lo2f(g.y) * v0[2], hi2f(g.y) * v0[3]};
;             f32x4 q1 = {lo2f(g.z) * v1[0], hi2f(g.z) * v1[1], lo2f(g.w) * v1[2], hi2f(g.w) * v1[3]};
;             st8(o0 + (size_t)(row0 + ai * 128 + m * 16) * DFF + col0 + bj * 128, q0, q1);
;           }
;         __builtin_amdgcn_sched_barrier(0);
;       }
; DI void conv_phase(const Params& p, int l) {
;     ...
;     for (int i = 0; i < RUN; ++i) {
;       unpack8(rows[i + 2], nxt);
;       float o[8];
; #pragma unroll
;       for (int j = 0; j < 8; ++j) { const float g = w0[j] * prev[j] + w1[j] * cur[j] + w2[j] * nxt[j] + bb[j]; o[j] = g * sigmoidf_(g); }
;       uint4 oo; oo.x = pack2(o[0], o[1]); oo.y = pack2(o[2], o[3]); oo.z = pack2(o[4], o[5]); oo.w = pack2(o[6], o[7]);
;       *(uint4*)(GS + (size_t)(t0 + i) * DFF + c0) = oo;
	v_lshlrev_b32_e32 v240, 16, v198
	v_and_b32_e32 v241, 0xffff0000, v198
	v_lshlrev_b32_e32 v242, 16, v202
	v_and_b32_e32 v243, 0xffff0000, v202
	v_lshlrev_b32_e32 v252, 16, v206
	v_and_b32_e32 v253, 0xffff0000, v206
	v_fma_f32 v254, v130, v240, v154
	v_fma_f32 v255, v131, v241, v155
	v_fma_f32 v254, v138, v242, v254
	v_fma_f32 v255, v139, v243, v255
	v_fma_f32 v254, v146, v252, v254
	v_fma_f32 v255, v147, v253, v255
	v_mul_f32_e32 v240, 0xbfb8aa3b, v254
	v_mul_f32_e32 v241, 0xbfb8aa3b, v255
	v_exp_f32_e32 v240, v240
	v_exp_f32_e32 v241, v241
	v_add_f32_e32 v240, 1.0, v240
	v_add_f32_e32 v241, 1.0, v241
	v_rcp_f32_e32 v240, v240
	v_rcp_f32_e32 v241, v241
	v_mul_f32_e32 v254, v254, v240
	v_mul_f32_e32 v255, v255, v241
	v_mul_f32_e32 v254, v254, v30
	v_mul_f32_e32 v255, v255, v31
	v_cvt_pk_bf16_f32 v248, v254, v255
	v_lshlrev_b32_e32 v240, 16, v199
	v_and_b32_e32 v241, 0xffff0000, v199
	v_lshlrev_b32_e32 v242, 16, v203
	v_and_b32_e32 v243, 0xffff0000, v203
	v_lshlrev_b32_e32 v252, 16, v207
	v_and_b32_e32 v253, 0xffff0000, v207
	v_fma_f32 v254, v132, v240, v156
	v_fma_f32 v255, v133, v241, v157
	v_fma_f32 v254, v140, v242, v254
	v_fma_f32 v255, v141, v243, v255
	v_fma_f32 v254, v148, v252, v254
	v_fma_f32 v255, v149, v253, v255
	v_mul_f32_e32 v240, 0xbfb8aa3b, v254
	v_mul_f32_e32 v241, 0xbfb8aa3b, v255
	v_exp_f32_e32 v240, v240
	v_exp_f32_e32 v241, v241
	v_add_f32_e32 v240, 1.0, v240
	v_add_f32_e32 v241, 1.0, v241
	v_rcp_f32_e32 v240, v240
	v_rcp_f32_e32 v241, v241
	v_mul_f32_e32 v254, v254, v240
	v_mul_f32_e32 v255, v255, v241
	v_mul_f32_e32 v254, v254, v32
	v_mul_f32_e32 v255, v255, v33
	v_cvt_pk_bf16_f32 v249, v254, v255
	v_lshlrev_b32_e32 v240, 16, v200
	v_and_b32_e32 v241, 0xffff0000, v200
	v_lshlrev_b32_e32 v242, 16, v204
	v_and_b32_e32 v243, 0xffff0000, v204
	v_lshlrev_b32_e32 v252, 16, v208
	v_and_b32_e32 v253, 0xffff0000, v208
	v_fma_f32 v254, v134, v240, v158
	v_fma_f32 v255, v135, v241, v159
	v_fma_f32 v254, v142, v242, v254
	v_fma_f32 v255, v143, v243, v255
	v_fma_f32 v254, v150, v252, v254
	v_fma_f32 v255, v151, v253, v255
	v_mul_f32_e32 v240, 0xbfb8aa3b, v254
	v_mul_f32_e32 v241, 0xbfb8aa3b, v255
	v_exp_f32_e32 v240, v240
	v_exp_f32_e32 v241, v241
	v_add_f32_e32 v240, 1.0, v240
	v_add_f32_e32 v241, 1.0, v241
	v_rcp_f32_e32 v240, v240
	v_rcp_f32_e32 v241, v241
	v_mul_f32_e32 v254, v254, v240
	v_mul_f32_e32 v255, v255, v241
	v_mul_f32_e32 v254, v254, v26
	v_mul_f32_e32 v255, v255, v27
	v_cvt_pk_bf16_f32 v250, v254, v255
	v_lshlrev_b32_e32 v240, 16, v201
	v_and_b32_e32 v241, 0xffff0000, v201
	v_lshlrev_b32_e32 v242, 16, v205
	v_and_b32_e32 v243, 0xffff0000, v205
	v_lshlrev_b32_e32 v252, 16, v209
	v_and_b32_e32 v253, 0xffff0000, v209
	v_fma_f32 v254, v136, v240, v160
	v_fma_f32 v255, v137, v241, v161
	v_fma_f32 v254, v144, v242, v254
	v_fma_f32 v255, v145, v243, v255
	v_fma_f32 v254, v152, v252, v254
	v_fma_f32 v255, v153, v253, v255
	v_mul_f32_e32 v240, 0xbfb8aa3b, v254
	v_mul_f32_e32 v241, 0xbfb8aa3b, v255
	v_exp_f32_e32 v240, v240
	v_exp_f32_e32 v241, v241
	v_add_f32_e32 v240, 1.0, v240
	v_add_f32_e32 v241, 1.0, v241
	v_rcp_f32_e32 v240, v240
	v_rcp_f32_e32 v241, v241
	v_mul_f32_e32 v254, v254, v240
	v_mul_f32_e32 v255, v255, v241
	v_mul_f32_e32 v254, v254, v28
	v_mul_f32_e32 v255, v255, v29
	v_cvt_pk_bf16_f32 v251, v254, v255
	global_store_dwordx4 v[220:221], v[248:251], off offset:256
	v_add_u32_e32 v183, 0xaf, v176
	v_mad_i64_i32 v[222:223], s[0:1], v183, s14, v[180:181]
	v_lshl_add_u64 v[224:225], v[222:223], 0, s[98:99]
	v_lshl_add_u64 v[226:227], v[224:225], 0, s[98:99]
	v_lshl_add_u64 v[220:221], v[224:225], 0, s[100:101]
	global_load_dwordx4 v[198:201], v[222:223], off offset:256
	global_load_dwordx4 v[202:205], v[224:225], off offset:256
	global_load_dwordx4 v[206:209], v[226:227], off offset:256
	s_waitcnt vmcnt(4)
; DI unsigned pack2(float a, float b) { f32x2_t v = {a, b}; bf16x2_t r = __builtin_convertvector(v, bf16x2_t); return __builtin_bit_cast(unsigned, r); }
; DI float lo2f(unsigned u) { return __uint_as_float(u << 16); }
; DI float hi2f(unsigned u) { return __uint_as_float(u & 0xffff0000u); }
; DI float sigmoidf_(float x) { return __builtin_amdgcn_rcpf(1.f + __builtin_amdgcn_exp2f(-1.4426950408889634f * x)); }
;   DI void operator()(const f32x4 (&acc)[2][2][4][2], const pg8::Unit& u, int wr, int wc, int fr, int fq) const {
;     ...
;     } else {
; #pragma unroll
;       for (int ai = 0; ai < 2; ++ai) {
;         uint4 gs[4][2];
; #pragma unroll
;         for (int m = 0; m < 4; ++m)
; #pragma unroll
;           for (int bj = 0; bj < 2; ++bj)
;             gs[m][bj] = *(const uint4*)(o0 + (size_t)(row0 + ai * 128 + m * 16) * DFF + col0 + bj * 128);
;         __builtin_amdgcn_sched_barrier(0);
; #pragma unroll
;         for (int m = 0; m < 4; ++m)
; #pragma unroll
;           for (int bj = 0; bj < 2; ++bj) {
;             const f32x4 v0 = acc[ai][bj][m][0], v1 = acc[ai][bj][m][1];
;             const uint4 g = gs[m][bj];
;             f32x4 q0 = {lo2f(g.x) * v0[0], hi2f(g.x) * v0[1], lo2f(g.y) * v0[2], hi2f(g.y) * v0[3]};
;             f32x4 q1 = {lo2f(g.z) * v1[0], hi2f(g.z) * v1[1], lo2f(g.w) * v1[2], hi2f(g.w) * v1[3]};
;             st8(o0 + (size_t)(row0 + ai * 128 + m * 16) * DFF + col0 + bj * 128, q0, q1);
;           }
;         __builtin_amdgcn_sched_barrier(0);
;       }
; DI void conv_phase(const Params& p, int l) {
;     ...
;     rows[RUN + 1] = (s0 + RUN - 1 < S - 1) ? *(const uint4*)(gp + (size_t)RUN * DFF) : z;
;     float w0[8], w1[8], w2[8], bb[8];
;     load8f(cw + c0, w0); load8f(cw + DFF + c0, w1); load8f(cw + 2 * DFF + c0, w2); load8f(cb + c0, bb);
;     float prev[8], cur[8], nxt[8];
;     unpack8(rows[0], prev); unpack8(rows[1], cur);
; #pragma unroll
;     for (int i = 0; i < RUN; ++i) {
;       unpack8(rows[i + 2], nxt);
;       float o[8];
; #pragma unroll
;       for (int j = 0; j < 8; ++j) { const float g = w0[j] * prev[j] + w1[j] * cur[j] + w2[j] * nxt[j] + bb[j]; o[j] = g * sigmoidf_(g); }
;       uint4 oo; oo.x = pack2(o[0], o[1]); oo.y = pack2(o[2], o[3]); oo.z = pack2(o[4], o[5]); oo.w = pack2(o[6], o[7]);
;       *(uint4*)(GS + (size_t)(t0 + i) * DFF + c0) = oo;
	v_lshlrev_b32_e32 v240, 16, v184
	v_and_b32_e32 v241, 0xffff0000, v184
	v_lshlrev_b32_e32 v242, 16, v188
	v_and_b32_e32 v243, 0xffff0000, v188
	v_lshlrev_b32_e32 v252, 16, v192
	v_and_b32_e32 v253, 0xffff0000, v192
	v_fma_f32 v254, v130, v240, v154
	v_fma_f32 v255, v131, v241, v155
	v_fma_f32 v254, v138, v242, v254
	v_fma_f32 v255, v139, v243, v255
	v_fma_f32 v254, v146, v252, v254
	v_fma_f32 v255, v147, v253, v255
	v_mul_f32_e32 v240, 0xbfb8aa3b, v254
	v_mul_f32_e32 v241, 0xbfb8aa3b, v255
	v_exp_f32_e32 v240, v240
	v_exp_f32_e32 v241, v241
	v_add_f32_e32 v240, 1.0, v240
	v_add_f32_e32 v241, 1.0, v241
	v_rcp_f32_e32 v240, v240
	v_rcp_f32_e32 v241, v241
	v_mul_f32_e32 v254, v254, v240
	v_mul_f32_e32 v255, v255, v241
	v_mul_f32_e32 v254, v254, v14
	v_mul_f32_e32 v255, v255, v15
	v_cvt_pk_bf16_f32 v244, v254, v255
	v_lshlrev_b32_e32 v240, 16, v185
	v_and_b32_e32 v241, 0xffff0000, v185
	v_lshlrev_b32_e32 v242, 16, v189
	v_and_b32_e32 v243, 0xffff0000, v189
	v_lshlrev_b32_e32 v252, 16, v193
	v_and_b32_e32 v253, 0xffff0000, v193
	v_fma_f32 v254, v132, v240, v156
	v_fma_f32 v255, v133, v241, v157
	v_fma_f32 v254, v140, v242, v254
	v_fma_f32 v255, v141, v243, v255
	v_fma_f32 v254, v148, v252, v254
	v_fma_f32 v255, v149, v253, v255
	v_mul_f32_e32 v240, 0xbfb8aa3b, v254
	v_mul_f32_e32 v241, 0xbfb8aa3b, v255
	v_exp_f32_e32 v240, v240
	v_exp_f32_e32 v241, v241
	v_add_f32_e32 v240, 1.0, v240
	v_add_f32_e32 v241, 1.0, v241
	v_rcp_f32_e32 v240, v240
	v_rcp_f32_e32 v241, v241
	v_mul_f32_e32 v254, v254, v240
	v_mul_f32_e32 v255, v255, v241
	v_mul_f32_e32 v254, v254, v16
	v_mul_f32_e32 v255, v255, v17
	v_cvt_pk_bf16_f32 v245, v254, v255
	v_lshlrev_b32_e32 v240, 16, v186
	v_and_b32_e32 v241, 0xffff0000, v186
	v_lshlrev_b32_e32 v242, 16, v190
	v_and_b32_e32 v243, 0xffff0000, v190
	v_lshlrev_b32_e32 v252, 16, v194
	v_and_b32_e32 v253, 0xffff0000, v194
	v_fma_f32 v254, v134, v240, v158
	v_fma_f32 v255, v135, v241, v159
	v_fma_f32 v254, v142, v242, v254
	v_fma_f32 v255, v143, v243, v255
	v_fma_f32 v254, v150, v252, v254
	v_fma_f32 v255, v151, v253, v255
	v_mul_f32_e32 v240, 0xbfb8aa3b, v254
	v_mul_f32_e32 v241, 0xbfb8aa3b, v255
	v_exp_f32_e32 v240, v240
	v_exp_f32_e32 v241, v241
	v_add_f32_e32 v240, 1.0, v240
	v_add_f32_e32 v241, 1.0, v241
	v_rcp_f32_e32 v240, v240
	v_rcp_f32_e32 v241, v241
	v_mul_f32_e32 v254, v254, v240
	v_mul_f32_e32 v255, v255, v241
	v_mul_f32_e32 v254, v254, v10
	v_mul_f32_e32 v255, v255, v11
	v_cvt_pk_bf16_f32 v246, v254, v255
	v_lshlrev_b32_e32 v240, 16, v187
	v_and_b32_e32 v241, 0xffff0000, v187
	v_lshlrev_b32_e32 v242, 16, v191
	v_and_b32_e32 v243, 0xffff0000, v191
	v_lshlrev_b32_e32 v252, 16, v195
	v_and_b32_e32 v253, 0xffff0000, v195
	v_fma_f32 v254, v136, v240, v160
	v_fma_f32 v255, v137, v241, v161
	v_fma_f32 v254, v144, v242, v254
	v_fma_f32 v255, v145, v243, v255
	v_fma_f32 v254, v152, v252, v254
	v_fma_f32 v255, v153, v253, v255
	v_mul_f32_e32 v240, 0xbfb8aa3b, v254
	v_mul_f32_e32 v241, 0xbfb8aa3b, v255
	v_exp_f32_e32 v240, v240
	v_exp_f32_e32 v241, v241
	v_add_f32_e32 v240, 1.0, v240
	v_add_f32_e32 v241, 1.0, v241
	v_rcp_f32_e32 v240, v240
	v_rcp_f32_e32 v241, v241
	v_mul_f32_e32 v254, v254, v240
	v_mul_f32_e32 v255, v255, v241
	v_mul_f32_e32 v254, v254, v12
	v_mul_f32_e32 v255, v255, v13
	v_cvt_pk_bf16_f32 v247, v254, v255
	global_store_dwordx4 v[196:197], v[244:247], off offset:256
	s_waitcnt vmcnt(1)
	v_add_u32_e32 v183, 0xb0, v176
	v_and_b32_e32 v183, 0x1fff, v183
	v_cmp_eq_u32_e32 vcc, 0x1fff, v183
	v_cndmask_b32_e64 v206, v206, 0, vcc
	v_cndmask_b32_e64 v207, v207, 0, vcc
	v_cndmask_b32_e64 v208, v208, 0, vcc
	v_cndmask_b32_e64 v209, v209, 0, vcc
	v_lshlrev_b32_e32 v240, 16, v198
	v_and_b32_e32 v241, 0xffff0000, v198
	v_lshlrev_b32_e32 v242, 16, v202
	v_and_b32_e32 v243, 0xffff0000, v202
	v_lshlrev_b32_e32 v252, 16, v206
	v_and_b32_e32 v253, 0xffff0000, v206
	v_fma_f32 v254, v130, v240, v154
	v_fma_f32 v255, v131, v241, v155
	v_fma_f32 v254, v138, v242, v254
	v_fma_f32 v255, v139, v243, v255
	v_fma_f32 v254, v146, v252, v254
	v_fma_f32 v255, v147, v253, v255
	v_mul_f32_e32 v240, 0xbfb8aa3b, v254
	v_mul_f32_e32 v241, 0xbfb8aa3b, v255
	v_exp_f32_e32 v240, v240
	v_exp_f32_e32 v241, v241
	v_add_f32_e32 v240, 1.0, v240
	v_add_f32_e32 v241, 1.0, v241
	v_rcp_f32_e32 v240, v240
	v_rcp_f32_e32 v241, v241
	v_mul_f32_e32 v254, v254, v240
	v_mul_f32_e32 v255, v255, v241
	v_mul_f32_e32 v254, v254, v6
	v_mul_f32_e32 v255, v255, v7
	v_cvt_pk_bf16_f32 v248, v254, v255
	v_lshlrev_b32_e32 v240, 16, v199
	v_and_b32_e32 v241, 0xffff0000, v199
	v_lshlrev_b32_e32 v242, 16, v203
	v_and_b32_e32 v243, 0xffff0000, v203
	v_lshlrev_b32_e32 v252, 16, v207
	v_and_b32_e32 v253, 0xffff0000, v207
	v_fma_f32 v254, v132, v240, v156
	v_fma_f32 v255, v133, v241, v157
	v_fma_f32 v254, v140, v242, v254
	v_fma_f32 v255, v141, v243, v255
	v_fma_f32 v254, v148, v252, v254
	v_fma_f32 v255, v149, v253, v255
	v_mul_f32_e32 v240, 0xbfb8aa3b, v254
	v_mul_f32_e32 v241, 0xbfb8aa3b, v255
	v_exp_f32_e32 v240, v240
	v_exp_f32_e32 v241, v241
	v_add_f32_e32 v240, 1.0, v240
	v_add_f32_e32 v241, 1.0, v241
	v_rcp_f32_e32 v240, v240
	v_rcp_f32_e32 v241, v241
	v_mul_f32_e32 v254, v254, v240
	v_mul_f32_e32 v255, v255, v241
	v_mul_f32_e32 v254, v254, v8
	v_mul_f32_e32 v255, v255, v9
	v_cvt_pk_bf16_f32 v249, v254, v255
	v_lshlrev_b32_e32 v240, 16, v200
	v_and_b32_e32 v241, 0xffff0000, v200
	v_lshlrev_b32_e32 v242, 16, v204
	v_and_b32_e32 v243, 0xffff0000, v204
	v_lshlrev_b32_e32 v252, 16, v208
	v_and_b32_e32 v253, 0xffff0000, v208
	v_fma_f32 v254, v134, v240, v158
	v_fma_f32 v255, v135, v241, v159
	v_fma_f32 v254, v142, v242, v254
	v_fma_f32 v255, v143, v243, v255
	v_fma_f32 v254, v150, v252, v254
	v_fma_f32 v255, v151, v253, v255
	v_mul_f32_e32 v240, 0xbfb8aa3b, v254
	v_mul_f32_e32 v241, 0xbfb8aa3b, v255
	v_exp_f32_e32 v240, v240
	v_exp_f32_e32 v241, v241
	v_add_f32_e32 v240, 1.0, v240
	v_add_f32_e32 v241, 1.0, v241
	v_rcp_f32_e32 v240, v240
	v_rcp_f32_e32 v241, v241
	v_mul_f32_e32 v254, v254, v240
	v_mul_f32_e32 v255, v255, v241
	v_mul_f32_e32 v254, v254, v2
	v_mul_f32_e32 v255, v255, v3
	v_cvt_pk_bf16_f32 v250, v254, v255
	v_lshlrev_b32_e32 v240, 16, v201
	v_and_b32_e32 v241, 0xffff0000, v201
	v_lshlrev_b32_e32 v242, 16, v205
	v_and_b32_e32 v243, 0xffff0000, v205
	v_lshlrev_b32_e32 v252, 16, v209
	v_and_b32_e32 v253, 0xffff0000, v209
	v_fma_f32 v254, v136, v240, v160
	v_fma_f32 v255, v137, v241, v161
	v_fma_f32 v254, v144, v242, v254
	v_fma_f32 v255, v145, v243, v255
	v_fma_f32 v254, v152, v252, v254
	v_fma_f32 v255, v153, v253, v255
	v_mul_f32_e32 v240, 0xbfb8aa3b, v254
	v_mul_f32_e32 v241, 0xbfb8aa3b, v255
	v_exp_f32_e32 v240, v240
	v_exp_f32_e32 v241, v241
	v_add_f32_e32 v240, 1.0, v240
	v_add_f32_e32 v241, 1.0, v241
	v_rcp_f32_e32 v240, v240
	v_rcp_f32_e32 v241, v241
	v_mul_f32_e32 v254, v254, v240
	v_mul_f32_e32 v255, v255, v241
	v_mul_f32_e32 v254, v254, v4
	v_mul_f32_e32 v255, v255, v5
	v_cvt_pk_bf16_f32 v251, v254, v255
	global_store_dwordx4 v[220:221], v[248:251], off offset:256
	s_mov_b64 s[0:1], 0
